# best + K-loops: drop the no-op setprio 0/1 pair in the middle of each MMA block and the redundant lgkmcnt(0) between the pre-MMA barrier and the first MFMA
# speedup vs baseline: 1.0095x; 1.0031x over previous
; #define PG8_STAGE(bufoff, gbase, voff) do { _Pragma("unroll") for (int _i = 0; _i < 2; ++_i) \
;         __builtin_amdgcn_global_load_lds((const unsigned*)((const char*)(gbase) + (voff)[_i]), (PG8_LAS unsigned*)(lds + (bufoff) + ldsw + _i * 8192), 16, 0, 0); } while (0)
; #define PG8_LDA(dst, b, h) do { _Pragma("unroll") for (int m = 0; m < 4; ++m) _Pragma("unroll") for (int k = 0; k < 2; ++k) dst[m][k] = *(const PG8_LAS bf16x8*)(lds + PG8_SA(b, h) + aoff + m * 2048 + k * 1024); } while (0)
; #define PG8_LDB(dst, b, h) do { _Pragma("unroll") for (int n = 0; n < 2; ++n) _Pragma("unroll") for (int k = 0; k < 2; ++k) dst[n][k] = *(const PG8_LAS bf16x8*)(lds + PG8_SB(b, h) + boff + n * 2048 + k * 1024); } while (0)
; #define PG8_MMA(ai, bj, At, Bt) do { __builtin_amdgcn_s_setprio(1); _Pragma("unroll") for (int m = 0; m < 4; ++m) _Pragma("unroll") for (int n = 0; n < 2; ++n) _Pragma("unroll") for (int k = 0; k < 2; ++k) \
;         acc[ai][bj][m][n] = __builtin_amdgcn_mfma_f32_16x16x32_bf16(Bt[n][k], At[m][k], acc[ai][bj][m][n], 0, 0, 0); __builtin_amdgcn_s_setprio(0); } while (0)
; #define PG8_WAIT_V(n) asm volatile("s_waitcnt vmcnt(" #n ")" ::: "memory")
; #define PG8_WAIT_L(n) asm volatile("s_waitcnt lgkmcnt(" #n ")" ::: "memory")
; template <class Epi, class Sched, bool ALIGN_EPI = false, bool SP2 = false>
; __device__ __forceinline__ void gemm_phase(PG8_LAS unsigned char* lds, const Gemm g, const Sched& S, const Epi& E) {
;     ...
;             const bool last = (t == nt - 2);
;             const char* a1 = cA + (size_t)(t + 1) * kstep;
;             const char* a2 = last ? nA : cA + (size_t)(t + 2) * kstep; const char* b2 = last ? nB : cB + (size_t)(t + 2) * kstep;
;             const char* a3 = a2 + kstep; const char* b3 = b2 + kstep;
;             if (last && has_next) S.a_ready(nxt);
;             if constexpr (SP2) {
;             PG8_LDB(B0, 0, 0); PG8_LDB(B1, 0, 1); PG8_SCHED; PG8_LDA(At, 0, 0); PG8_STAGE(PG8_SA(1, 1), a1 + hstep, voffA);
;             PG8_WAIT_V(8); PG8_WAIT_L(0); PG8_BAR; PG8_MMA(0, 0, At, B0); PG8_MMA(0, 1, At, B1); PG8_BAR; PG8_SCHED;
;             PG8_LDA(At, 0, 1); PG8_STAGE(PG8_SB(0, 0), b2, voffB); PG8_STAGE(PG8_SB(0, 1), b2 + hstep, voffB); PG8_STAGE(PG8_SA(0, 0), a2, voffA);
;             PG8_WAIT_V(8); PG8_WAIT_L(0); PG8_BAR; PG8_MMA(1, 0, At, B0); PG8_MMA(1, 1, At, B1); PG8_BAR; PG8_SCHED;
.LBB0_57:
	s_add_u32 s46, s44, 0xfff80080
	s_addc_u32 s47, s45, -1
	s_add_i32 s57, 0, 0x10000
	s_cmp_eq_u32 s56, 28
	s_cselect_b32 s49, s17, s47
	s_cselect_b32 s48, s25, s46
	v_add_u32_e32 v148, s57, v151
	s_cselect_b32 s47, s15, s55
	s_cselect_b32 s46, s43, s54
	s_add_i32 s60, 0, 0x14000
	ds_read_b128 v[140:143], v148
	ds_read_b128 v[144:147], v148 offset:1024
	ds_read_b128 v[174:177], v148 offset:2048
	ds_read_b128 v[178:181], v148 offset:3072
	v_add_u32_e32 v148, s60, v151
	ds_read_b128 v[182:185], v148
	ds_read_b128 v[186:189], v148 offset:1024
	ds_read_b128 v[190:193], v148 offset:2048
	ds_read_b128 v[194:197], v148 offset:3072
	v_lshl_add_u64 v[148:149], s[44:45], 0, v[136:137]
	s_add_i32 m0, s28, 0xc000
	ds_read_b128 v[198:201], v172
	ds_read_b128 v[202:205], v172 offset:1024
	ds_read_b128 v[206:209], v172 offset:2048
	ds_read_b128 v[210:213], v172 offset:3072
	ds_read_b128 v[220:223], v172 offset:4096
	ds_read_b128 v[224:227], v172 offset:5120
	ds_read_b128 v[228:231], v172 offset:6144
	ds_read_b128 v[232:235], v172 offset:7168
	global_load_lds_dwordx4 v[148:149], off
	v_lshl_add_u64 v[148:149], s[44:45], 0, v[138:139]
	s_add_i32 m0, s28, 0xe000
	s_nop 0
	global_load_lds_dwordx4 v[148:149], off
	s_waitcnt vmcnt(8)
	s_waitcnt lgkmcnt(0)
	s_setprio 1
	s_barrier
	v_mfma_f32_16x16x32_bf16 v[124:127], v[140:143], v[198:201], v[124:127]
	v_mfma_f32_16x16x32_bf16 v[120:123], v[174:177], v[198:201], v[120:123]
	v_mfma_f32_16x16x32_bf16 v[116:119], v[140:143], v[206:209], v[116:119]
	v_mfma_f32_16x16x32_bf16 v[112:115], v[174:177], v[206:209], v[112:115]
	v_mfma_f32_16x16x32_bf16 v[100:103], v[140:143], v[220:223], v[100:103]
	v_mfma_f32_16x16x32_bf16 v[96:99], v[174:177], v[220:223], v[96:99]
	v_mfma_f32_16x16x32_bf16 v[84:87], v[140:143], v[228:231], v[84:87]
	v_mfma_f32_16x16x32_bf16 v[80:83], v[174:177], v[228:231], v[80:83]
	v_mfma_f32_16x16x32_bf16 v[124:127], v[144:147], v[202:205], v[124:127]
	v_mfma_f32_16x16x32_bf16 v[120:123], v[178:181], v[202:205], v[120:123]
	v_mfma_f32_16x16x32_bf16 v[116:119], v[144:147], v[210:213], v[116:119]
	v_mfma_f32_16x16x32_bf16 v[112:115], v[178:181], v[210:213], v[112:115]
	v_mfma_f32_16x16x32_bf16 v[100:103], v[144:147], v[224:227], v[100:103]
	v_mfma_f32_16x16x32_bf16 v[96:99], v[178:181], v[224:227], v[96:99]
	v_mfma_f32_16x16x32_bf16 v[84:87], v[144:147], v[232:235], v[84:87]
	v_mfma_f32_16x16x32_bf16 v[80:83], v[178:181], v[232:235], v[80:83]
	v_mfma_f32_16x16x32_bf16 v[108:111], v[182:185], v[198:201], v[108:111]
	v_mfma_f32_16x16x32_bf16 v[104:107], v[190:193], v[198:201], v[104:107]
	v_mfma_f32_16x16x32_bf16 v[92:95], v[182:185], v[206:209], v[92:95]
	v_mfma_f32_16x16x32_bf16 v[88:91], v[190:193], v[206:209], v[88:91]
	v_mfma_f32_16x16x32_bf16 v[76:79], v[182:185], v[220:223], v[76:79]
	v_mfma_f32_16x16x32_bf16 v[72:75], v[190:193], v[220:223], v[72:75]
	v_mfma_f32_16x16x32_bf16 v[68:71], v[182:185], v[228:231], v[68:71]
	v_mfma_f32_16x16x32_bf16 v[64:67], v[190:193], v[228:231], v[64:67]
	v_mfma_f32_16x16x32_bf16 v[108:111], v[186:189], v[202:205], v[108:111]
	v_mfma_f32_16x16x32_bf16 v[104:107], v[194:197], v[202:205], v[104:107]
	v_mfma_f32_16x16x32_bf16 v[92:95], v[186:189], v[210:213], v[92:95]
	v_mfma_f32_16x16x32_bf16 v[88:91], v[194:197], v[210:213], v[88:91]
	v_mfma_f32_16x16x32_bf16 v[76:79], v[186:189], v[224:227], v[76:79]
	v_mfma_f32_16x16x32_bf16 v[72:75], v[194:197], v[224:227], v[72:75]
	v_mfma_f32_16x16x32_bf16 v[68:71], v[186:189], v[232:235], v[68:71]
	v_mfma_f32_16x16x32_bf16 v[64:67], v[194:197], v[232:235], v[64:67]
	s_setprio 0
	s_barrier
	s_add_i32 s57, s57, s26
	v_lshl_add_u64 v[148:149], s[46:47], 0, v[132:133]
	s_mov_b32 m0, s57
	ds_read_b128 v[198:201], v172 offset:16384
	ds_read_b128 v[202:205], v172 offset:17408
	ds_read_b128 v[206:209], v172 offset:18432
	ds_read_b128 v[210:213], v172 offset:19456
	ds_read_b128 v[220:223], v172 offset:20480
	ds_read_b128 v[224:227], v172 offset:21504
	ds_read_b128 v[228:231], v172 offset:22528
	ds_read_b128 v[232:235], v172 offset:23552
	global_load_lds_dwordx4 v[148:149], off
	s_add_i32 m0, s57, 0x2000
	s_add_u32 s58, s46, 0x80000
	v_lshl_add_u64 v[214:215], s[46:47], 0, v[128:129]
	s_addc_u32 s59, s47, 0
	s_add_i32 s57, s60, s26
	global_load_lds_dwordx4 v[214:215], off
	v_lshl_add_u64 v[236:237], s[58:59], 0, v[132:133]
	s_mov_b32 m0, s57
	v_lshl_add_u64 v[238:239], s[48:49], 0, v[130:131]
	global_load_lds_dwordx4 v[236:237], off
	v_lshl_add_u64 v[236:237], s[58:59], 0, v[128:129]
	s_add_i32 m0, s57, 0x2000
	s_nop 0
	global_load_lds_dwordx4 v[236:237], off
	v_lshl_add_u64 v[236:237], s[48:49], 0, v[134:135]
	s_mov_b32 m0, s28
	s_nop 0
	global_load_lds_dwordx4 v[236:237], off
	s_mov_b32 m0, s29
	s_nop 0
	global_load_lds_dwordx4 v[238:239], off
	s_waitcnt vmcnt(8)
	s_waitcnt lgkmcnt(0)
	s_setprio 1
	s_barrier
; #define PG8_STAGE(bufoff, gbase, voff) do { _Pragma("unroll") for (int _i = 0; _i < 2; ++_i) \
;         __builtin_amdgcn_global_load_lds((const unsigned*)((const char*)(gbase) + (voff)[_i]), (PG8_LAS unsigned*)(lds + (bufoff) + ldsw + _i * 8192), 16, 0, 0); } while (0)
; #define PG8_LDA(dst, b, h) do { _Pragma("unroll") for (int m = 0; m < 4; ++m) _Pragma("unroll") for (int k = 0; k < 2; ++k) dst[m][k] = *(const PG8_LAS bf16x8*)(lds + PG8_SA(b, h) + aoff + m * 2048 + k * 1024); } while (0)
; #define PG8_LDB(dst, b, h) do { _Pragma("unroll") for (int n = 0; n < 2; ++n) _Pragma("unroll") for (int k = 0; k < 2; ++k) dst[n][k] = *(const PG8_LAS bf16x8*)(lds + PG8_SB(b, h) + boff + n * 2048 + k * 1024); } while (0)
; #define PG8_MMA(ai, bj, At, Bt) do { __builtin_amdgcn_s_setprio(1); _Pragma("unroll") for (int m = 0; m < 4; ++m) _Pragma("unroll") for (int n = 0; n < 2; ++n) _Pragma("unroll") for (int k = 0; k < 2; ++k) \
;         acc[ai][bj][m][n] = __builtin_amdgcn_mfma_f32_16x16x32_bf16(Bt[n][k], At[m][k], acc[ai][bj][m][n], 0, 0, 0); __builtin_amdgcn_s_setprio(0); } while (0)
; #define PG8_WAIT_V(n) asm volatile("s_waitcnt vmcnt(" #n ")" ::: "memory")
; #define PG8_WAIT_L(n) asm volatile("s_waitcnt lgkmcnt(" #n ")" ::: "memory")
; #define PG8_BAR __builtin_amdgcn_s_barrier()
; #define PG8_SCHED __builtin_amdgcn_sched_barrier(0)
; template <class Epi, class Sched, bool ALIGN_EPI = false, bool SP2 = false>
; __device__ __forceinline__ void gemm_phase(PG8_LAS unsigned char* lds, const Gemm g, const Sched& S, const Epi& E) {
;     ...
;             PG8_WAIT_V(8); PG8_WAIT_L(0); PG8_BAR; PG8_MMA(1, 0, At, B0); PG8_MMA(1, 1, At, B1); PG8_BAR; PG8_SCHED;
;             PG8_LDB(B0, 1, 0); PG8_LDB(B1, 1, 1); PG8_SCHED; PG8_LDA(At, 1, 0); PG8_STAGE(PG8_SA(0, 1), a2 + hstep, voffA);
;             PG8_WAIT_V(8); PG8_WAIT_L(0); PG8_BAR; PG8_MMA(0, 0, At, B0); PG8_MMA(0, 1, At, B1); PG8_BAR; PG8_SCHED;
	v_mfma_f32_16x16x32_bf16 v[60:63], v[140:143], v[198:201], v[60:63]
	v_mfma_f32_16x16x32_bf16 v[56:59], v[174:177], v[198:201], v[56:59]
	v_mfma_f32_16x16x32_bf16 v[52:55], v[140:143], v[206:209], v[52:55]
	v_mfma_f32_16x16x32_bf16 v[48:51], v[174:177], v[206:209], v[48:51]
	v_mfma_f32_16x16x32_bf16 v[36:39], v[140:143], v[220:223], v[36:39]
	v_mfma_f32_16x16x32_bf16 v[32:35], v[174:177], v[220:223], v[32:35]
	v_mfma_f32_16x16x32_bf16 v[20:23], v[140:143], v[228:231], v[20:23]
	v_mfma_f32_16x16x32_bf16 v[16:19], v[174:177], v[228:231], v[16:19]
	v_mfma_f32_16x16x32_bf16 v[60:63], v[144:147], v[202:205], v[60:63]
	v_mfma_f32_16x16x32_bf16 v[56:59], v[178:181], v[202:205], v[56:59]
	v_mfma_f32_16x16x32_bf16 v[52:55], v[144:147], v[210:213], v[52:55]
	v_mfma_f32_16x16x32_bf16 v[48:51], v[178:181], v[210:213], v[48:51]
	v_mfma_f32_16x16x32_bf16 v[36:39], v[144:147], v[224:227], v[36:39]
	v_mfma_f32_16x16x32_bf16 v[32:35], v[178:181], v[224:227], v[32:35]
	v_mfma_f32_16x16x32_bf16 v[20:23], v[144:147], v[232:235], v[20:23]
	v_mfma_f32_16x16x32_bf16 v[16:19], v[178:181], v[232:235], v[16:19]
	v_mfma_f32_16x16x32_bf16 v[44:47], v[182:185], v[198:201], v[44:47]
	v_mfma_f32_16x16x32_bf16 v[40:43], v[190:193], v[198:201], v[40:43]
	v_mfma_f32_16x16x32_bf16 v[28:31], v[182:185], v[206:209], v[28:31]
	v_mfma_f32_16x16x32_bf16 v[24:27], v[190:193], v[206:209], v[24:27]
	v_mfma_f32_16x16x32_bf16 v[12:15], v[182:185], v[220:223], v[12:15]
	v_mfma_f32_16x16x32_bf16 v[8:11], v[190:193], v[220:223], v[8:11]
	v_mfma_f32_16x16x32_bf16 v[4:7], v[182:185], v[228:231], v[4:7]
	v_mfma_f32_16x16x32_bf16 v[0:3], v[190:193], v[228:231], v[0:3]
	v_mfma_f32_16x16x32_bf16 v[44:47], v[186:189], v[202:205], v[44:47]
	v_mfma_f32_16x16x32_bf16 v[40:43], v[194:197], v[202:205], v[40:43]
	v_mfma_f32_16x16x32_bf16 v[28:31], v[186:189], v[210:213], v[28:31]
	v_mfma_f32_16x16x32_bf16 v[24:27], v[194:197], v[210:213], v[24:27]
	v_mfma_f32_16x16x32_bf16 v[12:15], v[186:189], v[224:227], v[12:15]
	v_mfma_f32_16x16x32_bf16 v[8:11], v[194:197], v[224:227], v[8:11]
	v_mfma_f32_16x16x32_bf16 v[4:7], v[186:189], v[232:235], v[4:7]
	v_mfma_f32_16x16x32_bf16 v[0:3], v[194:197], v[232:235], v[0:3]
	s_setprio 0
	s_barrier
	s_add_i32 s57, 0, 0x18000
	v_add_u32_e32 v152, s57, v151
	s_add_i32 s58, 0, 0x1c000
	ds_read_b128 v[140:143], v152
	ds_read_b128 v[144:147], v152 offset:1024
	ds_read_b128 v[174:177], v152 offset:2048
	ds_read_b128 v[178:181], v152 offset:3072
	v_add_u32_e32 v152, s58, v151
	ds_read_b128 v[182:185], v152
	ds_read_b128 v[186:189], v152 offset:1024
	ds_read_b128 v[190:193], v152 offset:2048
	ds_read_b128 v[194:197], v152 offset:3072
	s_add_u32 s48, s48, 0x80000
	s_addc_u32 s49, s49, 0
	s_mov_b32 m0, s33
	v_lshl_add_u64 v[240:241], s[48:49], 0, v[134:135]
	ds_read_b128 v[198:201], v172 offset:32768
	ds_read_b128 v[202:205], v172 offset:33792
	ds_read_b128 v[206:209], v172 offset:34816
	ds_read_b128 v[210:213], v172 offset:35840
	ds_read_b128 v[220:223], v172 offset:36864
	ds_read_b128 v[224:227], v172 offset:37888
	ds_read_b128 v[228:231], v172 offset:38912
	ds_read_b128 v[232:235], v172 offset:39936
	global_load_lds_dwordx4 v[240:241], off
	v_lshl_add_u64 v[240:241], s[48:49], 0, v[130:131]
	s_mov_b32 m0, s50
	s_nop 0
	global_load_lds_dwordx4 v[240:241], off
	s_waitcnt vmcnt(8)
	s_waitcnt lgkmcnt(0)
	s_setprio 1
	s_barrier
	v_mfma_f32_16x16x32_bf16 v[124:127], v[140:143], v[198:201], v[124:127]
	v_mfma_f32_16x16x32_bf16 v[120:123], v[174:177], v[198:201], v[120:123]
	v_mfma_f32_16x16x32_bf16 v[116:119], v[140:143], v[206:209], v[116:119]
	v_mfma_f32_16x16x32_bf16 v[112:115], v[174:177], v[206:209], v[112:115]
	v_mfma_f32_16x16x32_bf16 v[100:103], v[140:143], v[220:223], v[100:103]
	v_mfma_f32_16x16x32_bf16 v[96:99], v[174:177], v[220:223], v[96:99]
	v_mfma_f32_16x16x32_bf16 v[84:87], v[140:143], v[228:231], v[84:87]
	v_mfma_f32_16x16x32_bf16 v[80:83], v[174:177], v[228:231], v[80:83]
	v_mfma_f32_16x16x32_bf16 v[124:127], v[144:147], v[202:205], v[124:127]
	v_mfma_f32_16x16x32_bf16 v[120:123], v[178:181], v[202:205], v[120:123]
	v_mfma_f32_16x16x32_bf16 v[116:119], v[144:147], v[210:213], v[116:119]
	v_mfma_f32_16x16x32_bf16 v[112:115], v[178:181], v[210:213], v[112:115]
	v_mfma_f32_16x16x32_bf16 v[100:103], v[144:147], v[224:227], v[100:103]
	v_mfma_f32_16x16x32_bf16 v[96:99], v[178:181], v[224:227], v[96:99]
	v_mfma_f32_16x16x32_bf16 v[84:87], v[144:147], v[232:235], v[84:87]
	v_mfma_f32_16x16x32_bf16 v[80:83], v[178:181], v[232:235], v[80:83]
	v_mfma_f32_16x16x32_bf16 v[108:111], v[182:185], v[198:201], v[108:111]
	v_mfma_f32_16x16x32_bf16 v[104:107], v[190:193], v[198:201], v[104:107]
	v_mfma_f32_16x16x32_bf16 v[92:95], v[182:185], v[206:209], v[92:95]
	v_mfma_f32_16x16x32_bf16 v[88:91], v[190:193], v[206:209], v[88:91]
	v_mfma_f32_16x16x32_bf16 v[76:79], v[182:185], v[220:223], v[76:79]
	v_mfma_f32_16x16x32_bf16 v[72:75], v[190:193], v[220:223], v[72:75]
	v_mfma_f32_16x16x32_bf16 v[68:71], v[182:185], v[228:231], v[68:71]
	v_mfma_f32_16x16x32_bf16 v[64:67], v[190:193], v[228:231], v[64:67]
	v_mfma_f32_16x16x32_bf16 v[108:111], v[186:189], v[202:205], v[108:111]
	v_mfma_f32_16x16x32_bf16 v[104:107], v[194:197], v[202:205], v[104:107]
	v_mfma_f32_16x16x32_bf16 v[92:95], v[186:189], v[210:213], v[92:95]
	v_mfma_f32_16x16x32_bf16 v[88:91], v[194:197], v[210:213], v[88:91]
	v_mfma_f32_16x16x32_bf16 v[76:79], v[186:189], v[224:227], v[76:79]
	v_mfma_f32_16x16x32_bf16 v[72:75], v[194:197], v[224:227], v[72:75]
	v_mfma_f32_16x16x32_bf16 v[68:71], v[186:189], v[232:235], v[68:71]
	v_mfma_f32_16x16x32_bf16 v[64:67], v[194:197], v[232:235], v[64:67]
	s_setprio 0
	s_barrier
; #define PG8_STAGE(bufoff, gbase, voff) do { _Pragma("unroll") for (int _i = 0; _i < 2; ++_i) \
;         __builtin_amdgcn_global_load_lds((const unsigned*)((const char*)(gbase) + (voff)[_i]), (PG8_LAS unsigned*)(lds + (bufoff) + ldsw + _i * 8192), 16, 0, 0); } while (0)
; #define PG8_LDA(dst, b, h) do { _Pragma("unroll") for (int m = 0; m < 4; ++m) _Pragma("unroll") for (int k = 0; k < 2; ++k) dst[m][k] = *(const PG8_LAS bf16x8*)(lds + PG8_SA(b, h) + aoff + m * 2048 + k * 1024); } while (0)
; #define PG8_MMA(ai, bj, At, Bt) do { __builtin_amdgcn_s_setprio(1); _Pragma("unroll") for (int m = 0; m < 4; ++m) _Pragma("unroll") for (int n = 0; n < 2; ++n) _Pragma("unroll") for (int k = 0; k < 2; ++k) \
;         acc[ai][bj][m][n] = __builtin_amdgcn_mfma_f32_16x16x32_bf16(Bt[n][k], At[m][k], acc[ai][bj][m][n], 0, 0, 0); __builtin_amdgcn_s_setprio(0); } while (0)
; #define PG8_WAIT_V(n) asm volatile("s_waitcnt vmcnt(" #n ")" ::: "memory")
; #define PG8_WAIT_L(n) asm volatile("s_waitcnt lgkmcnt(" #n ")" ::: "memory")
; #define PG8_BAR __builtin_amdgcn_s_barrier()
; #define PG8_SCHED __builtin_amdgcn_sched_barrier(0)
; template <class Epi, class Sched, bool ALIGN_EPI = false, bool SP2 = false>
; __device__ __forceinline__ void gemm_phase(PG8_LAS unsigned char* lds, const Gemm g, const Sched& S, const Epi& E) {
;     ...
;             PG8_LDA(At, 1, 1); PG8_STAGE(PG8_SB(1, 0), b3, voffB); PG8_STAGE(PG8_SB(1, 1), b3 + hstep, voffB); PG8_STAGE(PG8_SA(1, 0), a3, voffA);
;             PG8_WAIT_V(8); PG8_WAIT_L(0); PG8_BAR; PG8_MMA(1, 0, At, B0); PG8_MMA(1, 1, At, B1); PG8_BAR; PG8_SCHED;
	s_add_i32 s48, s57, s26
	v_lshl_add_u64 v[148:149], v[148:149], 0, s[90:91]
	s_mov_b32 m0, s48
	ds_read_b128 v[198:201], v172 offset:49152
	ds_read_b128 v[202:205], v172 offset:50176
	ds_read_b128 v[206:209], v172 offset:51200
	ds_read_b128 v[210:213], v172 offset:52224
	ds_read_b128 v[220:223], v172 offset:53248
	ds_read_b128 v[224:227], v172 offset:54272
	ds_read_b128 v[228:231], v172 offset:55296
	ds_read_b128 v[232:235], v172 offset:56320
	global_load_lds_dwordx4 v[148:149], off
	s_add_i32 m0, s48, 0x2000
	s_add_u32 s46, s46, 0x80080
	v_lshl_add_u64 v[148:149], v[214:215], 0, s[90:91]
	s_addc_u32 s47, s47, 0
	s_add_i32 s48, s58, s26
	global_load_lds_dwordx4 v[148:149], off
	v_lshl_add_u64 v[148:149], s[46:47], 0, v[132:133]
	s_mov_b32 m0, s48
	s_nop 0
	global_load_lds_dwordx4 v[148:149], off
	v_lshl_add_u64 v[148:149], s[46:47], 0, v[128:129]
	s_add_i32 m0, s48, 0x2000
	s_nop 0
	global_load_lds_dwordx4 v[148:149], off
	v_lshl_add_u64 v[148:149], v[236:237], 0, s[90:91]
	s_mov_b32 m0, s4
	s_nop 0
	global_load_lds_dwordx4 v[148:149], off
	v_lshl_add_u64 v[148:149], v[238:239], 0, s[90:91]
	s_mov_b32 m0, s51
	s_nop 0
	global_load_lds_dwordx4 v[148:149], off
	s_waitcnt vmcnt(8)
	s_waitcnt lgkmcnt(0)
	s_setprio 1
	s_barrier
	v_mfma_f32_16x16x32_bf16 v[60:63], v[140:143], v[198:201], v[60:63]
	v_mfma_f32_16x16x32_bf16 v[56:59], v[174:177], v[198:201], v[56:59]
	v_mfma_f32_16x16x32_bf16 v[52:55], v[140:143], v[206:209], v[52:55]
	v_mfma_f32_16x16x32_bf16 v[48:51], v[174:177], v[206:209], v[48:51]
	v_mfma_f32_16x16x32_bf16 v[36:39], v[140:143], v[220:223], v[36:39]
	v_mfma_f32_16x16x32_bf16 v[32:35], v[174:177], v[220:223], v[32:35]
	v_mfma_f32_16x16x32_bf16 v[20:23], v[140:143], v[228:231], v[20:23]
	v_mfma_f32_16x16x32_bf16 v[16:19], v[174:177], v[228:231], v[16:19]
	v_mfma_f32_16x16x32_bf16 v[60:63], v[144:147], v[202:205], v[60:63]
	v_mfma_f32_16x16x32_bf16 v[56:59], v[178:181], v[202:205], v[56:59]
	v_mfma_f32_16x16x32_bf16 v[52:55], v[144:147], v[210:213], v[52:55]
	v_mfma_f32_16x16x32_bf16 v[48:51], v[178:181], v[210:213], v[48:51]
	v_mfma_f32_16x16x32_bf16 v[36:39], v[144:147], v[224:227], v[36:39]
	v_mfma_f32_16x16x32_bf16 v[32:35], v[178:181], v[224:227], v[32:35]
	v_mfma_f32_16x16x32_bf16 v[20:23], v[144:147], v[232:235], v[20:23]
	v_mfma_f32_16x16x32_bf16 v[16:19], v[178:181], v[232:235], v[16:19]
	v_mfma_f32_16x16x32_bf16 v[44:47], v[182:185], v[198:201], v[44:47]
	v_mfma_f32_16x16x32_bf16 v[40:43], v[190:193], v[198:201], v[40:43]
	v_mfma_f32_16x16x32_bf16 v[28:31], v[182:185], v[206:209], v[28:31]
	v_mfma_f32_16x16x32_bf16 v[24:27], v[190:193], v[206:209], v[24:27]
	v_mfma_f32_16x16x32_bf16 v[12:15], v[182:185], v[220:223], v[12:15]
	v_mfma_f32_16x16x32_bf16 v[8:11], v[190:193], v[220:223], v[8:11]
	v_mfma_f32_16x16x32_bf16 v[4:7], v[182:185], v[228:231], v[4:7]
	v_mfma_f32_16x16x32_bf16 v[0:3], v[190:193], v[228:231], v[0:3]
	v_mfma_f32_16x16x32_bf16 v[44:47], v[186:189], v[202:205], v[44:47]
	v_mfma_f32_16x16x32_bf16 v[40:43], v[194:197], v[202:205], v[40:43]
	v_mfma_f32_16x16x32_bf16 v[28:31], v[186:189], v[210:213], v[28:31]
	v_mfma_f32_16x16x32_bf16 v[24:27], v[194:197], v[210:213], v[24:27]
	v_mfma_f32_16x16x32_bf16 v[12:15], v[186:189], v[224:227], v[12:15]
	v_mfma_f32_16x16x32_bf16 v[8:11], v[194:197], v[224:227], v[8:11]
	v_mfma_f32_16x16x32_bf16 v[4:7], v[186:189], v[232:235], v[4:7]
	v_mfma_f32_16x16x32_bf16 v[0:3], v[194:197], v[232:235], v[0:3]
	s_setprio 0
	s_barrier
	s_add_i32 s56, s56, 2
	s_add_u32 s44, s44, 0x100
	s_addc_u32 s45, s45, 0
	s_add_u32 s54, s54, 0x100
	s_addc_u32 s55, s55, 0
	s_cmp_gt_u32 s56, 29
	s_cbranch_scc0 .LBB0_57
	s_and_b64 vcc, exec, s[12:13]
	s_cbranch_vccz .LBB0_60
	s_barrier

; #define PG8_STAGE(bufoff, gbase, voff) do { _Pragma("unroll") for (int _i = 0; _i < 2; ++_i) \
;         __builtin_amdgcn_global_load_lds((const unsigned*)((const char*)(gbase) + (voff)[_i]), (PG8_LAS unsigned*)(lds + (bufoff) + ldsw + _i * 8192), 16, 0, 0); } while (0)
; #define PG8_LDA(dst, b, h) do { _Pragma("unroll") for (int m = 0; m < 4; ++m) _Pragma("unroll") for (int k = 0; k < 2; ++k) dst[m][k] = *(const PG8_LAS bf16x8*)(lds + PG8_SA(b, h) + aoff + m * 2048 + k * 1024); } while (0)
; #define PG8_LDB(dst, b, h) do { _Pragma("unroll") for (int n = 0; n < 2; ++n) _Pragma("unroll") for (int k = 0; k < 2; ++k) dst[n][k] = *(const PG8_LAS bf16x8*)(lds + PG8_SB(b, h) + boff + n * 2048 + k * 1024); } while (0)
; #define PG8_MMA(ai, bj, At, Bt) do { __builtin_amdgcn_s_setprio(1); _Pragma("unroll") for (int m = 0; m < 4; ++m) _Pragma("unroll") for (int n = 0; n < 2; ++n) _Pragma("unroll") for (int k = 0; k < 2; ++k) \
;         acc[ai][bj][m][n] = __builtin_amdgcn_mfma_f32_16x16x32_bf16(Bt[n][k], At[m][k], acc[ai][bj][m][n], 0, 0, 0); __builtin_amdgcn_s_setprio(0); } while (0)
; #define PG8_WAIT_V(n) asm volatile("s_waitcnt vmcnt(" #n ")" ::: "memory")
; #define PG8_WAIT_L(n) asm volatile("s_waitcnt lgkmcnt(" #n ")" ::: "memory")
; template <class Epi, class Sched, bool ALIGN_EPI = false, bool SP2 = false>
; __device__ __forceinline__ void gemm_phase(PG8_LAS unsigned char* lds, const Gemm g, const Sched& S, const Epi& E) {
;     ...
;             const bool last = (t == nt - 2);
;             const char* a1 = cA + (size_t)(t + 1) * kstep;
;             const char* a2 = last ? nA : cA + (size_t)(t + 2) * kstep; const char* b2 = last ? nB : cB + (size_t)(t + 2) * kstep;
;             const char* a3 = a2 + kstep; const char* b3 = b2 + kstep;
;             if (last && has_next) S.a_ready(nxt);
;             if constexpr (SP2) {
;             PG8_LDB(B0, 0, 0); PG8_LDB(B1, 0, 1); PG8_SCHED; PG8_LDA(At, 0, 0); PG8_STAGE(PG8_SA(1, 1), a1 + hstep, voffA);
;             PG8_WAIT_V(8); PG8_WAIT_L(0); PG8_BAR; PG8_MMA(0, 0, At, B0); PG8_MMA(0, 1, At, B1); PG8_BAR; PG8_SCHED;
;             PG8_LDA(At, 0, 1); PG8_STAGE(PG8_SB(0, 0), b2, voffB); PG8_STAGE(PG8_SB(0, 1), b2 + hstep, voffB); PG8_STAGE(PG8_SA(0, 0), a2, voffA);
;             PG8_WAIT_V(8); PG8_WAIT_L(0); PG8_BAR; PG8_MMA(1, 0, At, B0); PG8_MMA(1, 1, At, B1); PG8_BAR; PG8_SCHED;
.LBB0_231:
	s_add_u32 s33, s42, 0xfff80080
	s_addc_u32 s44, s43, -1
	s_add_i32 s57, 0, 0x10000
	s_cmp_eq_u32 s29, 28
	s_cselect_b32 s47, s13, s44
	s_cselect_b32 s46, s25, s33
	s_cselect_b32 s45, s11, s28
	s_cselect_b32 s44, s26, s27
	s_add_i32 s33, 0, 0x14000
	v_add_u32_e32 v140, s57, v192
	v_add_u32_e32 v188, s33, v192
	ds_read_b128 v[128:131], v140
	ds_read_b128 v[132:135], v140 offset:1024
	ds_read_b128 v[136:139], v140 offset:2048
	ds_read_b128 v[140:143], v140 offset:3072
	ds_read_b128 v[176:179], v188
	ds_read_b128 v[180:183], v188 offset:1024
	ds_read_b128 v[184:187], v188 offset:2048
	ds_read_b128 v[198:201], v188 offset:3072
	v_lshl_add_u64 v[188:189], s[42:43], 0, v[172:173]
	s_add_i32 m0, s50, 0xc000
	ds_read_b128 v[202:205], v197
	ds_read_b128 v[206:209], v197 offset:1024
	ds_read_b128 v[210:213], v197 offset:2048
	ds_read_b128 v[220:223], v197 offset:3072
	ds_read_b128 v[224:227], v197 offset:4096
	ds_read_b128 v[228:231], v197 offset:5120
	ds_read_b128 v[232:235], v197 offset:6144
	ds_read_b128 v[236:239], v197 offset:7168
	global_load_lds_dwordx4 v[188:189], off
	v_lshl_add_u64 v[188:189], s[42:43], 0, v[174:175]
	s_add_i32 m0, s50, 0xe000
	s_nop 0
	global_load_lds_dwordx4 v[188:189], off
	s_waitcnt vmcnt(8)
	s_waitcnt lgkmcnt(0)
	s_setprio 1
	s_barrier
	v_mfma_f32_16x16x32_bf16 v[124:127], v[128:131], v[202:205], v[124:127]
	v_mfma_f32_16x16x32_bf16 v[120:123], v[136:139], v[202:205], v[120:123]
	v_mfma_f32_16x16x32_bf16 v[116:119], v[128:131], v[210:213], v[116:119]
	v_mfma_f32_16x16x32_bf16 v[112:115], v[136:139], v[210:213], v[112:115]
	v_mfma_f32_16x16x32_bf16 v[100:103], v[128:131], v[224:227], v[100:103]
	v_mfma_f32_16x16x32_bf16 v[96:99], v[136:139], v[224:227], v[96:99]
	v_mfma_f32_16x16x32_bf16 v[84:87], v[128:131], v[232:235], v[84:87]
	v_mfma_f32_16x16x32_bf16 v[80:83], v[136:139], v[232:235], v[80:83]
	v_mfma_f32_16x16x32_bf16 v[124:127], v[132:135], v[206:209], v[124:127]
	v_mfma_f32_16x16x32_bf16 v[120:123], v[140:143], v[206:209], v[120:123]
	v_mfma_f32_16x16x32_bf16 v[116:119], v[132:135], v[220:223], v[116:119]
	v_mfma_f32_16x16x32_bf16 v[112:115], v[140:143], v[220:223], v[112:115]
	v_mfma_f32_16x16x32_bf16 v[100:103], v[132:135], v[228:231], v[100:103]
	v_mfma_f32_16x16x32_bf16 v[96:99], v[140:143], v[228:231], v[96:99]
	v_mfma_f32_16x16x32_bf16 v[84:87], v[132:135], v[236:239], v[84:87]
	v_mfma_f32_16x16x32_bf16 v[80:83], v[140:143], v[236:239], v[80:83]
	v_mfma_f32_16x16x32_bf16 v[108:111], v[176:179], v[202:205], v[108:111]
	v_mfma_f32_16x16x32_bf16 v[104:107], v[184:187], v[202:205], v[104:107]
	v_mfma_f32_16x16x32_bf16 v[92:95], v[176:179], v[210:213], v[92:95]
	v_mfma_f32_16x16x32_bf16 v[88:91], v[184:187], v[210:213], v[88:91]
	v_mfma_f32_16x16x32_bf16 v[76:79], v[176:179], v[224:227], v[76:79]
	v_mfma_f32_16x16x32_bf16 v[72:75], v[184:187], v[224:227], v[72:75]
	v_mfma_f32_16x16x32_bf16 v[68:71], v[176:179], v[232:235], v[68:71]
	v_mfma_f32_16x16x32_bf16 v[64:67], v[184:187], v[232:235], v[64:67]
	v_mfma_f32_16x16x32_bf16 v[108:111], v[180:183], v[206:209], v[108:111]
	v_mfma_f32_16x16x32_bf16 v[104:107], v[198:201], v[206:209], v[104:107]
	v_mfma_f32_16x16x32_bf16 v[92:95], v[180:183], v[220:223], v[92:95]
	v_mfma_f32_16x16x32_bf16 v[88:91], v[198:201], v[220:223], v[88:91]
	v_mfma_f32_16x16x32_bf16 v[76:79], v[180:183], v[228:231], v[76:79]
	v_mfma_f32_16x16x32_bf16 v[72:75], v[198:201], v[228:231], v[72:75]
	v_mfma_f32_16x16x32_bf16 v[68:71], v[180:183], v[236:239], v[68:71]
	v_mfma_f32_16x16x32_bf16 v[64:67], v[198:201], v[236:239], v[64:67]
	s_setprio 0
	s_barrier
	s_add_i32 s57, s57, s48
	v_lshl_add_u64 v[188:189], s[44:45], 0, v[152:153]
	s_mov_b32 m0, s57
	ds_read_b128 v[202:205], v197 offset:16384
	ds_read_b128 v[206:209], v197 offset:17408
	ds_read_b128 v[210:213], v197 offset:18432
	ds_read_b128 v[220:223], v197 offset:19456
	ds_read_b128 v[224:227], v197 offset:20480
	ds_read_b128 v[228:231], v197 offset:21504
	ds_read_b128 v[232:235], v197 offset:22528
	ds_read_b128 v[236:239], v197 offset:23552
	global_load_lds_dwordx4 v[188:189], off
	s_add_i32 m0, s57, 0x2000
	s_add_u32 s58, s44, 0x80000
	v_lshl_add_u64 v[214:215], s[44:45], 0, v[144:145]
	s_addc_u32 s59, s45, 0
	s_add_i32 s33, s33, s48
	global_load_lds_dwordx4 v[214:215], off
	v_lshl_add_u64 v[240:241], s[58:59], 0, v[152:153]
	s_mov_b32 m0, s33
	v_lshl_add_u64 v[242:243], s[46:47], 0, v[146:147]
	global_load_lds_dwordx4 v[240:241], off
	v_lshl_add_u64 v[240:241], s[58:59], 0, v[144:145]
	s_add_i32 m0, s33, 0x2000
	s_nop 0
	global_load_lds_dwordx4 v[240:241], off
	v_lshl_add_u64 v[240:241], s[46:47], 0, v[148:149]
	s_mov_b32 m0, s50
	s_nop 0
	global_load_lds_dwordx4 v[240:241], off
	s_mov_b32 m0, s51
	s_nop 0
	global_load_lds_dwordx4 v[242:243], off
	s_waitcnt vmcnt(8)
	s_waitcnt lgkmcnt(0)
	s_setprio 1
	s_barrier
; #define PG8_STAGE(bufoff, gbase, voff) do { _Pragma("unroll") for (int _i = 0; _i < 2; ++_i) \
;         __builtin_amdgcn_global_load_lds((const unsigned*)((const char*)(gbase) + (voff)[_i]), (PG8_LAS unsigned*)(lds + (bufoff) + ldsw + _i * 8192), 16, 0, 0); } while (0)
; #define PG8_LDA(dst, b, h) do { _Pragma("unroll") for (int m = 0; m < 4; ++m) _Pragma("unroll") for (int k = 0; k < 2; ++k) dst[m][k] = *(const PG8_LAS bf16x8*)(lds + PG8_SA(b, h) + aoff + m * 2048 + k * 1024); } while (0)
; #define PG8_LDB(dst, b, h) do { _Pragma("unroll") for (int n = 0; n < 2; ++n) _Pragma("unroll") for (int k = 0; k < 2; ++k) dst[n][k] = *(const PG8_LAS bf16x8*)(lds + PG8_SB(b, h) + boff + n * 2048 + k * 1024); } while (0)
; #define PG8_MMA(ai, bj, At, Bt) do { __builtin_amdgcn_s_setprio(1); _Pragma("unroll") for (int m = 0; m < 4; ++m) _Pragma("unroll") for (int n = 0; n < 2; ++n) _Pragma("unroll") for (int k = 0; k < 2; ++k) \
;         acc[ai][bj][m][n] = __builtin_amdgcn_mfma_f32_16x16x32_bf16(Bt[n][k], At[m][k], acc[ai][bj][m][n], 0, 0, 0); __builtin_amdgcn_s_setprio(0); } while (0)
; #define PG8_WAIT_V(n) asm volatile("s_waitcnt vmcnt(" #n ")" ::: "memory")
; #define PG8_WAIT_L(n) asm volatile("s_waitcnt lgkmcnt(" #n ")" ::: "memory")
; #define PG8_BAR __builtin_amdgcn_s_barrier()
; #define PG8_SCHED __builtin_amdgcn_sched_barrier(0)
; template <class Epi, class Sched, bool ALIGN_EPI = false, bool SP2 = false>
; __device__ __forceinline__ void gemm_phase(PG8_LAS unsigned char* lds, const Gemm g, const Sched& S, const Epi& E) {
;     ...
;             PG8_WAIT_V(8); PG8_WAIT_L(0); PG8_BAR; PG8_MMA(1, 0, At, B0); PG8_MMA(1, 1, At, B1); PG8_BAR; PG8_SCHED;
;             PG8_LDB(B0, 1, 0); PG8_LDB(B1, 1, 1); PG8_SCHED; PG8_LDA(At, 1, 0); PG8_STAGE(PG8_SA(0, 1), a2 + hstep, voffA);
;             PG8_WAIT_V(8); PG8_WAIT_L(0); PG8_BAR; PG8_MMA(0, 0, At, B0); PG8_MMA(0, 1, At, B1); PG8_BAR; PG8_SCHED;
	v_mfma_f32_16x16x32_bf16 v[60:63], v[128:131], v[202:205], v[60:63]
	v_mfma_f32_16x16x32_bf16 v[56:59], v[136:139], v[202:205], v[56:59]
	v_mfma_f32_16x16x32_bf16 v[52:55], v[128:131], v[210:213], v[52:55]
	v_mfma_f32_16x16x32_bf16 v[48:51], v[136:139], v[210:213], v[48:51]
	v_mfma_f32_16x16x32_bf16 v[36:39], v[128:131], v[224:227], v[36:39]
	v_mfma_f32_16x16x32_bf16 v[32:35], v[136:139], v[224:227], v[32:35]
	v_mfma_f32_16x16x32_bf16 v[20:23], v[128:131], v[232:235], v[20:23]
	v_mfma_f32_16x16x32_bf16 v[16:19], v[136:139], v[232:235], v[16:19]
	v_mfma_f32_16x16x32_bf16 v[60:63], v[132:135], v[206:209], v[60:63]
	v_mfma_f32_16x16x32_bf16 v[56:59], v[140:143], v[206:209], v[56:59]
	v_mfma_f32_16x16x32_bf16 v[52:55], v[132:135], v[220:223], v[52:55]
	v_mfma_f32_16x16x32_bf16 v[48:51], v[140:143], v[220:223], v[48:51]
	v_mfma_f32_16x16x32_bf16 v[36:39], v[132:135], v[228:231], v[36:39]
	v_mfma_f32_16x16x32_bf16 v[32:35], v[140:143], v[228:231], v[32:35]
	v_mfma_f32_16x16x32_bf16 v[20:23], v[132:135], v[236:239], v[20:23]
	v_mfma_f32_16x16x32_bf16 v[16:19], v[140:143], v[236:239], v[16:19]
	v_mfma_f32_16x16x32_bf16 v[44:47], v[176:179], v[202:205], v[44:47]
	v_mfma_f32_16x16x32_bf16 v[40:43], v[184:187], v[202:205], v[40:43]
	v_mfma_f32_16x16x32_bf16 v[28:31], v[176:179], v[210:213], v[28:31]
	v_mfma_f32_16x16x32_bf16 v[24:27], v[184:187], v[210:213], v[24:27]
	v_mfma_f32_16x16x32_bf16 v[12:15], v[176:179], v[224:227], v[12:15]
	v_mfma_f32_16x16x32_bf16 v[8:11], v[184:187], v[224:227], v[8:11]
	v_mfma_f32_16x16x32_bf16 v[4:7], v[176:179], v[232:235], v[4:7]
	v_mfma_f32_16x16x32_bf16 v[0:3], v[184:187], v[232:235], v[0:3]
	v_mfma_f32_16x16x32_bf16 v[44:47], v[180:183], v[206:209], v[44:47]
	v_mfma_f32_16x16x32_bf16 v[40:43], v[198:201], v[206:209], v[40:43]
	v_mfma_f32_16x16x32_bf16 v[28:31], v[180:183], v[220:223], v[28:31]
	v_mfma_f32_16x16x32_bf16 v[24:27], v[198:201], v[220:223], v[24:27]
	v_mfma_f32_16x16x32_bf16 v[12:15], v[180:183], v[228:231], v[12:15]
	v_mfma_f32_16x16x32_bf16 v[8:11], v[198:201], v[228:231], v[8:11]
	v_mfma_f32_16x16x32_bf16 v[4:7], v[180:183], v[236:239], v[4:7]
	v_mfma_f32_16x16x32_bf16 v[0:3], v[198:201], v[236:239], v[0:3]
	s_setprio 0
	s_barrier
	s_add_i32 s33, 0, 0x18000
	s_add_i32 s57, 0, 0x1c000
	v_add_u32_e32 v140, s33, v192
	v_add_u32_e32 v198, s57, v192
	ds_read_b128 v[128:131], v140
	ds_read_b128 v[132:135], v140 offset:1024
	ds_read_b128 v[136:139], v140 offset:2048
	ds_read_b128 v[140:143], v140 offset:3072
	ds_read_b128 v[176:179], v198
	ds_read_b128 v[180:183], v198 offset:1024
	ds_read_b128 v[184:187], v198 offset:2048
	ds_read_b128 v[198:201], v198 offset:3072
	s_add_u32 s46, s46, 0x80000
	s_addc_u32 s47, s47, 0
	s_mov_b32 m0, s52
	v_lshl_add_u64 v[244:245], s[46:47], 0, v[148:149]
	ds_read_b128 v[202:205], v197 offset:32768
	ds_read_b128 v[206:209], v197 offset:33792
	ds_read_b128 v[210:213], v197 offset:34816
	ds_read_b128 v[220:223], v197 offset:35840
	ds_read_b128 v[224:227], v197 offset:36864
	ds_read_b128 v[228:231], v197 offset:37888
	ds_read_b128 v[232:235], v197 offset:38912
	ds_read_b128 v[236:239], v197 offset:39936
	global_load_lds_dwordx4 v[244:245], off
	v_lshl_add_u64 v[244:245], s[46:47], 0, v[146:147]
	s_mov_b32 m0, s53
	s_nop 0
	global_load_lds_dwordx4 v[244:245], off
	s_waitcnt vmcnt(8)
	s_waitcnt lgkmcnt(0)
	s_setprio 1
	s_barrier
	v_mfma_f32_16x16x32_bf16 v[124:127], v[128:131], v[202:205], v[124:127]
	v_mfma_f32_16x16x32_bf16 v[120:123], v[136:139], v[202:205], v[120:123]
	v_mfma_f32_16x16x32_bf16 v[116:119], v[128:131], v[210:213], v[116:119]
	v_mfma_f32_16x16x32_bf16 v[112:115], v[136:139], v[210:213], v[112:115]
	v_mfma_f32_16x16x32_bf16 v[100:103], v[128:131], v[224:227], v[100:103]
	v_mfma_f32_16x16x32_bf16 v[96:99], v[136:139], v[224:227], v[96:99]
	v_mfma_f32_16x16x32_bf16 v[84:87], v[128:131], v[232:235], v[84:87]
	v_mfma_f32_16x16x32_bf16 v[80:83], v[136:139], v[232:235], v[80:83]
	v_mfma_f32_16x16x32_bf16 v[124:127], v[132:135], v[206:209], v[124:127]
	v_mfma_f32_16x16x32_bf16 v[120:123], v[140:143], v[206:209], v[120:123]
	v_mfma_f32_16x16x32_bf16 v[116:119], v[132:135], v[220:223], v[116:119]
	v_mfma_f32_16x16x32_bf16 v[112:115], v[140:143], v[220:223], v[112:115]
	v_mfma_f32_16x16x32_bf16 v[100:103], v[132:135], v[228:231], v[100:103]
	v_mfma_f32_16x16x32_bf16 v[96:99], v[140:143], v[228:231], v[96:99]
	v_mfma_f32_16x16x32_bf16 v[84:87], v[132:135], v[236:239], v[84:87]
	v_mfma_f32_16x16x32_bf16 v[80:83], v[140:143], v[236:239], v[80:83]
	v_mfma_f32_16x16x32_bf16 v[108:111], v[176:179], v[202:205], v[108:111]
	v_mfma_f32_16x16x32_bf16 v[104:107], v[184:187], v[202:205], v[104:107]
	v_mfma_f32_16x16x32_bf16 v[92:95], v[176:179], v[210:213], v[92:95]
	v_mfma_f32_16x16x32_bf16 v[88:91], v[184:187], v[210:213], v[88:91]
	v_mfma_f32_16x16x32_bf16 v[76:79], v[176:179], v[224:227], v[76:79]
	v_mfma_f32_16x16x32_bf16 v[72:75], v[184:187], v[224:227], v[72:75]
	v_mfma_f32_16x16x32_bf16 v[68:71], v[176:179], v[232:235], v[68:71]
	v_mfma_f32_16x16x32_bf16 v[64:67], v[184:187], v[232:235], v[64:67]
	v_mfma_f32_16x16x32_bf16 v[108:111], v[180:183], v[206:209], v[108:111]
	v_mfma_f32_16x16x32_bf16 v[104:107], v[198:201], v[206:209], v[104:107]
	v_mfma_f32_16x16x32_bf16 v[92:95], v[180:183], v[220:223], v[92:95]
	v_mfma_f32_16x16x32_bf16 v[88:91], v[198:201], v[220:223], v[88:91]
	v_mfma_f32_16x16x32_bf16 v[76:79], v[180:183], v[228:231], v[76:79]
	v_mfma_f32_16x16x32_bf16 v[72:75], v[198:201], v[228:231], v[72:75]
	v_mfma_f32_16x16x32_bf16 v[68:71], v[180:183], v[236:239], v[68:71]
	v_mfma_f32_16x16x32_bf16 v[64:67], v[198:201], v[236:239], v[64:67]
	s_setprio 0
	s_barrier
; #define PG8_STAGE(bufoff, gbase, voff) do { _Pragma("unroll") for (int _i = 0; _i < 2; ++_i) \
;         __builtin_amdgcn_global_load_lds((const unsigned*)((const char*)(gbase) + (voff)[_i]), (PG8_LAS unsigned*)(lds + (bufoff) + ldsw + _i * 8192), 16, 0, 0); } while (0)
; #define PG8_LDA(dst, b, h) do { _Pragma("unroll") for (int m = 0; m < 4; ++m) _Pragma("unroll") for (int k = 0; k < 2; ++k) dst[m][k] = *(const PG8_LAS bf16x8*)(lds + PG8_SA(b, h) + aoff + m * 2048 + k * 1024); } while (0)
; #define PG8_MMA(ai, bj, At, Bt) do { __builtin_amdgcn_s_setprio(1); _Pragma("unroll") for (int m = 0; m < 4; ++m) _Pragma("unroll") for (int n = 0; n < 2; ++n) _Pragma("unroll") for (int k = 0; k < 2; ++k) \
;         acc[ai][bj][m][n] = __builtin_amdgcn_mfma_f32_16x16x32_bf16(Bt[n][k], At[m][k], acc[ai][bj][m][n], 0, 0, 0); __builtin_amdgcn_s_setprio(0); } while (0)
; #define PG8_WAIT_V(n) asm volatile("s_waitcnt vmcnt(" #n ")" ::: "memory")
; #define PG8_WAIT_L(n) asm volatile("s_waitcnt lgkmcnt(" #n ")" ::: "memory")
; #define PG8_BAR __builtin_amdgcn_s_barrier()
; #define PG8_SCHED __builtin_amdgcn_sched_barrier(0)
; template <class Epi, class Sched, bool ALIGN_EPI = false, bool SP2 = false>
; __device__ __forceinline__ void gemm_phase(PG8_LAS unsigned char* lds, const Gemm g, const Sched& S, const Epi& E) {
;     ...
;             PG8_LDA(At, 1, 1); PG8_STAGE(PG8_SB(1, 0), b3, voffB); PG8_STAGE(PG8_SB(1, 1), b3 + hstep, voffB); PG8_STAGE(PG8_SA(1, 0), a3, voffA);
;             PG8_WAIT_V(8); PG8_WAIT_L(0); PG8_BAR; PG8_MMA(1, 0, At, B0); PG8_MMA(1, 1, At, B1); PG8_BAR; PG8_SCHED;
	s_add_i32 s33, s33, s48
	v_lshl_add_u64 v[188:189], v[188:189], 0, s[90:91]
	s_mov_b32 m0, s33
	ds_read_b128 v[202:205], v197 offset:49152
	ds_read_b128 v[206:209], v197 offset:50176
	ds_read_b128 v[210:213], v197 offset:51200
	ds_read_b128 v[220:223], v197 offset:52224
	ds_read_b128 v[224:227], v197 offset:53248
	ds_read_b128 v[228:231], v197 offset:54272
	ds_read_b128 v[232:235], v197 offset:55296
	ds_read_b128 v[236:239], v197 offset:56320
	global_load_lds_dwordx4 v[188:189], off
	s_add_i32 m0, s33, 0x2000
	s_add_u32 s44, s44, 0x80080
	v_lshl_add_u64 v[188:189], v[214:215], 0, s[90:91]
	s_addc_u32 s45, s45, 0
	s_add_i32 s33, s57, s48
	global_load_lds_dwordx4 v[188:189], off
	v_lshl_add_u64 v[188:189], s[44:45], 0, v[152:153]
	s_mov_b32 m0, s33
	s_nop 0
	global_load_lds_dwordx4 v[188:189], off
	v_lshl_add_u64 v[188:189], s[44:45], 0, v[144:145]
	s_add_i32 m0, s33, 0x2000
	s_nop 0
	global_load_lds_dwordx4 v[188:189], off
	v_lshl_add_u64 v[188:189], v[240:241], 0, s[90:91]
	s_mov_b32 m0, s4
	s_nop 0
	global_load_lds_dwordx4 v[188:189], off
	v_lshl_add_u64 v[188:189], v[242:243], 0, s[90:91]
	s_mov_b32 m0, s54
	s_nop 0
	global_load_lds_dwordx4 v[188:189], off
	s_waitcnt vmcnt(8)
	s_waitcnt lgkmcnt(0)
	s_setprio 1
	s_barrier
	v_mfma_f32_16x16x32_bf16 v[60:63], v[128:131], v[202:205], v[60:63]
	v_mfma_f32_16x16x32_bf16 v[56:59], v[136:139], v[202:205], v[56:59]
	v_mfma_f32_16x16x32_bf16 v[52:55], v[128:131], v[210:213], v[52:55]
	v_mfma_f32_16x16x32_bf16 v[48:51], v[136:139], v[210:213], v[48:51]
	v_mfma_f32_16x16x32_bf16 v[36:39], v[128:131], v[224:227], v[36:39]
	v_mfma_f32_16x16x32_bf16 v[32:35], v[136:139], v[224:227], v[32:35]
	v_mfma_f32_16x16x32_bf16 v[20:23], v[128:131], v[232:235], v[20:23]
	v_mfma_f32_16x16x32_bf16 v[16:19], v[136:139], v[232:235], v[16:19]
	v_mfma_f32_16x16x32_bf16 v[60:63], v[132:135], v[206:209], v[60:63]
	v_mfma_f32_16x16x32_bf16 v[56:59], v[140:143], v[206:209], v[56:59]
	v_mfma_f32_16x16x32_bf16 v[52:55], v[132:135], v[220:223], v[52:55]
	v_mfma_f32_16x16x32_bf16 v[48:51], v[140:143], v[220:223], v[48:51]
	v_mfma_f32_16x16x32_bf16 v[36:39], v[132:135], v[228:231], v[36:39]
	v_mfma_f32_16x16x32_bf16 v[32:35], v[140:143], v[228:231], v[32:35]
	v_mfma_f32_16x16x32_bf16 v[20:23], v[132:135], v[236:239], v[20:23]
	v_mfma_f32_16x16x32_bf16 v[16:19], v[140:143], v[236:239], v[16:19]
	v_mfma_f32_16x16x32_bf16 v[44:47], v[176:179], v[202:205], v[44:47]
	v_mfma_f32_16x16x32_bf16 v[40:43], v[184:187], v[202:205], v[40:43]
	v_mfma_f32_16x16x32_bf16 v[28:31], v[176:179], v[210:213], v[28:31]
	v_mfma_f32_16x16x32_bf16 v[24:27], v[184:187], v[210:213], v[24:27]
	v_mfma_f32_16x16x32_bf16 v[12:15], v[176:179], v[224:227], v[12:15]
	v_mfma_f32_16x16x32_bf16 v[8:11], v[184:187], v[224:227], v[8:11]
	v_mfma_f32_16x16x32_bf16 v[4:7], v[176:179], v[232:235], v[4:7]
	v_mfma_f32_16x16x32_bf16 v[0:3], v[184:187], v[232:235], v[0:3]
	v_mfma_f32_16x16x32_bf16 v[44:47], v[180:183], v[206:209], v[44:47]
	v_mfma_f32_16x16x32_bf16 v[40:43], v[198:201], v[206:209], v[40:43]
	v_mfma_f32_16x16x32_bf16 v[28:31], v[180:183], v[220:223], v[28:31]
	v_mfma_f32_16x16x32_bf16 v[24:27], v[198:201], v[220:223], v[24:27]
	v_mfma_f32_16x16x32_bf16 v[12:15], v[180:183], v[228:231], v[12:15]
	v_mfma_f32_16x16x32_bf16 v[8:11], v[198:201], v[228:231], v[8:11]
	v_mfma_f32_16x16x32_bf16 v[4:7], v[180:183], v[236:239], v[4:7]
	v_mfma_f32_16x16x32_bf16 v[0:3], v[198:201], v[236:239], v[0:3]
	s_setprio 0
	s_barrier
	s_add_i32 s29, s29, 2
	s_add_u32 s42, s42, 0x100
	s_addc_u32 s43, s43, 0
	s_add_u32 s27, s27, 0x100
	s_addc_u32 s28, s28, 0
	s_cmp_gt_u32 s29, 29
	s_cbranch_scc0 .LBB0_231
	s_and_b64 vcc, exec, s[8:9]
	s_cbranch_vccz .LBB0_234
	s_barrier

; #define PG8_STAGE(bufoff, gbase, voff) do { _Pragma("unroll") for (int _i = 0; _i < 2; ++_i) \
;         __builtin_amdgcn_global_load_lds((const unsigned*)((const char*)(gbase) + (voff)[_i]), (PG8_LAS unsigned*)(lds + (bufoff) + ldsw + _i * 8192), 16, 0, 0); } while (0)
; #define PG8_LDA(dst, b, h) do { _Pragma("unroll") for (int m = 0; m < 4; ++m) _Pragma("unroll") for (int k = 0; k < 2; ++k) dst[m][k] = *(const PG8_LAS bf16x8*)(lds + PG8_SA(b, h) + aoff + m * 2048 + k * 1024); } while (0)
; #define PG8_LDB(dst, b, h) do { _Pragma("unroll") for (int n = 0; n < 2; ++n) _Pragma("unroll") for (int k = 0; k < 2; ++k) dst[n][k] = *(const PG8_LAS bf16x8*)(lds + PG8_SB(b, h) + boff + n * 2048 + k * 1024); } while (0)
; #define PG8_MMA(ai, bj, At, Bt) do { __builtin_amdgcn_s_setprio(1); _Pragma("unroll") for (int m = 0; m < 4; ++m) _Pragma("unroll") for (int n = 0; n < 2; ++n) _Pragma("unroll") for (int k = 0; k < 2; ++k) \
;         acc[ai][bj][m][n] = __builtin_amdgcn_mfma_f32_16x16x32_bf16(Bt[n][k], At[m][k], acc[ai][bj][m][n], 0, 0, 0); __builtin_amdgcn_s_setprio(0); } while (0)
; #define PG8_WAIT_V(n) asm volatile("s_waitcnt vmcnt(" #n ")" ::: "memory")
; #define PG8_WAIT_L(n) asm volatile("s_waitcnt lgkmcnt(" #n ")" ::: "memory")
; template <class Epi, class Sched, bool ALIGN_EPI = false, bool SP2 = false>
; __device__ __forceinline__ void gemm_phase(PG8_LAS unsigned char* lds, const Gemm g, const Sched& S, const Epi& E) {
;     ...
;             const bool last = (t == nt - 2);
;             const char* a1 = cA + (size_t)(t + 1) * kstep;
;             const char* a2 = last ? nA : cA + (size_t)(t + 2) * kstep; const char* b2 = last ? nB : cB + (size_t)(t + 2) * kstep;
;             const char* a3 = a2 + kstep; const char* b3 = b2 + kstep;
;             if (last && has_next) S.a_ready(nxt);
;             if constexpr (SP2) {
;             PG8_LDB(B0, 0, 0); PG8_LDB(B1, 0, 1); PG8_SCHED; PG8_LDA(At, 0, 0); PG8_STAGE(PG8_SA(1, 1), a1 + hstep, voffA);
;             PG8_WAIT_V(8); PG8_WAIT_L(0); PG8_BAR; PG8_MMA(0, 0, At, B0); PG8_MMA(0, 1, At, B1); PG8_BAR; PG8_SCHED;
;             PG8_LDA(At, 0, 1); PG8_STAGE(PG8_SB(0, 0), b2, voffB); PG8_STAGE(PG8_SB(0, 1), b2 + hstep, voffB); PG8_STAGE(PG8_SA(0, 0), a2, voffA);
;             PG8_WAIT_V(8); PG8_WAIT_L(0); PG8_BAR; PG8_MMA(1, 0, At, B0); PG8_MMA(1, 1, At, B1); PG8_BAR; PG8_SCHED;
.LBB0_291:
	s_add_u32 s18, s16, 0x14aba100
	s_addc_u32 s19, s17, 0
	s_add_u32 s44, s16, s41
	s_addc_u32 s45, s17, s42
	s_cmp_eq_u32 s43, 28
	s_cselect_b32 s39, s89, s19
	s_cselect_b32 s38, s88, s18
	s_cselect_b32 s19, s15, s45
	s_cselect_b32 s18, s14, s44
	s_add_i32 s44, 0, 0x10000
	v_add_u32_e32 v150, s44, v140
	s_add_i32 s46, 0, 0x14000
	ds_read_b128 v[142:145], v150
	ds_read_b128 v[146:149], v150 offset:1024
	ds_read_b128 v[170:173], v150 offset:2048
	ds_read_b128 v[174:177], v150 offset:3072
	v_add_u32_e32 v150, s46, v140
	ds_read_b128 v[178:181], v150
	ds_read_b128 v[182:185], v150 offset:1024
	ds_read_b128 v[186:189], v150 offset:2048
	ds_read_b128 v[190:193], v150 offset:3072
	v_lshl_add_u64 v[150:151], s[16:17], 0, v[134:135]
	s_add_i32 m0, s13, 0xc000
	ds_read_b128 v[194:197], v141
	ds_read_b128 v[198:201], v141 offset:1024
	ds_read_b128 v[202:205], v141 offset:2048
	ds_read_b128 v[206:209], v141 offset:3072
	ds_read_b128 v[210:213], v141 offset:4096
	ds_read_b128 v[220:223], v141 offset:5120
	ds_read_b128 v[224:227], v141 offset:6144
	ds_read_b128 v[228:231], v141 offset:7168
	global_load_lds_dwordx4 v[150:151], off
	v_lshl_add_u64 v[150:151], s[16:17], 0, v[136:137]
	s_add_i32 m0, s13, 0xe000
	s_nop 0
	global_load_lds_dwordx4 v[150:151], off
	s_waitcnt vmcnt(8)
	s_waitcnt lgkmcnt(0)
	s_setprio 1
	s_barrier
	v_mfma_f32_16x16x32_bf16 v[124:127], v[142:145], v[194:197], v[124:127]
	v_mfma_f32_16x16x32_bf16 v[120:123], v[170:173], v[194:197], v[120:123]
	v_mfma_f32_16x16x32_bf16 v[108:111], v[142:145], v[202:205], v[108:111]
	v_mfma_f32_16x16x32_bf16 v[104:107], v[170:173], v[202:205], v[104:107]
	v_mfma_f32_16x16x32_bf16 v[92:95], v[142:145], v[210:213], v[92:95]
	v_mfma_f32_16x16x32_bf16 v[88:91], v[170:173], v[210:213], v[88:91]
	v_mfma_f32_16x16x32_bf16 v[76:79], v[142:145], v[224:227], v[76:79]
	v_mfma_f32_16x16x32_bf16 v[72:75], v[170:173], v[224:227], v[72:75]
	v_mfma_f32_16x16x32_bf16 v[124:127], v[146:149], v[198:201], v[124:127]
	v_mfma_f32_16x16x32_bf16 v[120:123], v[174:177], v[198:201], v[120:123]
	v_mfma_f32_16x16x32_bf16 v[108:111], v[146:149], v[206:209], v[108:111]
	v_mfma_f32_16x16x32_bf16 v[104:107], v[174:177], v[206:209], v[104:107]
	v_mfma_f32_16x16x32_bf16 v[92:95], v[146:149], v[220:223], v[92:95]
	v_mfma_f32_16x16x32_bf16 v[88:91], v[174:177], v[220:223], v[88:91]
	v_mfma_f32_16x16x32_bf16 v[76:79], v[146:149], v[228:231], v[76:79]
	v_mfma_f32_16x16x32_bf16 v[72:75], v[174:177], v[228:231], v[72:75]
	v_mfma_f32_16x16x32_bf16 v[116:119], v[178:181], v[194:197], v[116:119]
	v_mfma_f32_16x16x32_bf16 v[112:115], v[186:189], v[194:197], v[112:115]
	v_mfma_f32_16x16x32_bf16 v[100:103], v[178:181], v[202:205], v[100:103]
	v_mfma_f32_16x16x32_bf16 v[96:99], v[186:189], v[202:205], v[96:99]
	v_mfma_f32_16x16x32_bf16 v[84:87], v[178:181], v[210:213], v[84:87]
	v_mfma_f32_16x16x32_bf16 v[80:83], v[186:189], v[210:213], v[80:83]
	v_mfma_f32_16x16x32_bf16 v[68:71], v[178:181], v[224:227], v[68:71]
	v_mfma_f32_16x16x32_bf16 v[64:67], v[186:189], v[224:227], v[64:67]
	v_mfma_f32_16x16x32_bf16 v[116:119], v[182:185], v[198:201], v[116:119]
	v_mfma_f32_16x16x32_bf16 v[112:115], v[190:193], v[198:201], v[112:115]
	v_mfma_f32_16x16x32_bf16 v[100:103], v[182:185], v[206:209], v[100:103]
	v_mfma_f32_16x16x32_bf16 v[96:99], v[190:193], v[206:209], v[96:99]
	v_mfma_f32_16x16x32_bf16 v[84:87], v[182:185], v[220:223], v[84:87]
	v_mfma_f32_16x16x32_bf16 v[80:83], v[190:193], v[220:223], v[80:83]
	v_mfma_f32_16x16x32_bf16 v[68:71], v[182:185], v[228:231], v[68:71]
	v_mfma_f32_16x16x32_bf16 v[64:67], v[190:193], v[228:231], v[64:67]
	s_setprio 0
	s_barrier
	s_add_i32 s44, s44, s26
	v_lshl_add_u64 v[150:151], s[18:19], 0, v[152:153]
	s_mov_b32 m0, s44
	ds_read_b128 v[194:197], v141 offset:16384
	ds_read_b128 v[198:201], v141 offset:17408
	ds_read_b128 v[202:205], v141 offset:18432
	ds_read_b128 v[206:209], v141 offset:19456
	ds_read_b128 v[210:213], v141 offset:20480
	ds_read_b128 v[220:223], v141 offset:21504
	ds_read_b128 v[224:227], v141 offset:22528
	ds_read_b128 v[228:231], v141 offset:23552
	global_load_lds_dwordx4 v[150:151], off
	s_add_i32 m0, s44, 0x2000
	s_add_u32 s44, s18, 0x80000
	v_lshl_add_u64 v[214:215], s[18:19], 0, v[128:129]
	s_addc_u32 s45, s19, 0
	s_add_i32 s46, s46, s26
	global_load_lds_dwordx4 v[214:215], off
	v_lshl_add_u64 v[232:233], s[44:45], 0, v[152:153]
	s_mov_b32 m0, s46
	v_lshl_add_u64 v[234:235], s[38:39], 0, v[130:131]
	global_load_lds_dwordx4 v[232:233], off
	v_lshl_add_u64 v[232:233], s[44:45], 0, v[128:129]
	s_add_i32 m0, s46, 0x2000
	s_nop 0
	global_load_lds_dwordx4 v[232:233], off
	v_lshl_add_u64 v[232:233], s[38:39], 0, v[132:133]
	s_mov_b32 m0, s13
	s_nop 0
	global_load_lds_dwordx4 v[232:233], off
	s_mov_b32 m0, s27
	s_nop 0
	global_load_lds_dwordx4 v[234:235], off
	s_waitcnt vmcnt(8)
	s_waitcnt lgkmcnt(0)
	s_setprio 1
	s_barrier
; #define PG8_STAGE(bufoff, gbase, voff) do { _Pragma("unroll") for (int _i = 0; _i < 2; ++_i) \
;         __builtin_amdgcn_global_load_lds((const unsigned*)((const char*)(gbase) + (voff)[_i]), (PG8_LAS unsigned*)(lds + (bufoff) + ldsw + _i * 8192), 16, 0, 0); } while (0)
; #define PG8_LDA(dst, b, h) do { _Pragma("unroll") for (int m = 0; m < 4; ++m) _Pragma("unroll") for (int k = 0; k < 2; ++k) dst[m][k] = *(const PG8_LAS bf16x8*)(lds + PG8_SA(b, h) + aoff + m * 2048 + k * 1024); } while (0)
; #define PG8_LDB(dst, b, h) do { _Pragma("unroll") for (int n = 0; n < 2; ++n) _Pragma("unroll") for (int k = 0; k < 2; ++k) dst[n][k] = *(const PG8_LAS bf16x8*)(lds + PG8_SB(b, h) + boff + n * 2048 + k * 1024); } while (0)
; #define PG8_MMA(ai, bj, At, Bt) do { __builtin_amdgcn_s_setprio(1); _Pragma("unroll") for (int m = 0; m < 4; ++m) _Pragma("unroll") for (int n = 0; n < 2; ++n) _Pragma("unroll") for (int k = 0; k < 2; ++k) \
;         acc[ai][bj][m][n] = __builtin_amdgcn_mfma_f32_16x16x32_bf16(Bt[n][k], At[m][k], acc[ai][bj][m][n], 0, 0, 0); __builtin_amdgcn_s_setprio(0); } while (0)
; #define PG8_WAIT_V(n) asm volatile("s_waitcnt vmcnt(" #n ")" ::: "memory")
; #define PG8_WAIT_L(n) asm volatile("s_waitcnt lgkmcnt(" #n ")" ::: "memory")
; #define PG8_BAR __builtin_amdgcn_s_barrier()
; #define PG8_SCHED __builtin_amdgcn_sched_barrier(0)
; template <class Epi, class Sched, bool ALIGN_EPI = false, bool SP2 = false>
; __device__ __forceinline__ void gemm_phase(PG8_LAS unsigned char* lds, const Gemm g, const Sched& S, const Epi& E) {
;     ...
;             PG8_WAIT_V(8); PG8_WAIT_L(0); PG8_BAR; PG8_MMA(1, 0, At, B0); PG8_MMA(1, 1, At, B1); PG8_BAR; PG8_SCHED;
;             PG8_LDB(B0, 1, 0); PG8_LDB(B1, 1, 1); PG8_SCHED; PG8_LDA(At, 1, 0); PG8_STAGE(PG8_SA(0, 1), a2 + hstep, voffA);
;             PG8_WAIT_V(8); PG8_WAIT_L(0); PG8_BAR; PG8_MMA(0, 0, At, B0); PG8_MMA(0, 1, At, B1); PG8_BAR; PG8_SCHED;
	v_mfma_f32_16x16x32_bf16 v[60:63], v[142:145], v[194:197], v[60:63]
	v_mfma_f32_16x16x32_bf16 v[56:59], v[170:173], v[194:197], v[56:59]
	v_mfma_f32_16x16x32_bf16 v[44:47], v[142:145], v[202:205], v[44:47]
	v_mfma_f32_16x16x32_bf16 v[40:43], v[170:173], v[202:205], v[40:43]
	v_mfma_f32_16x16x32_bf16 v[28:31], v[142:145], v[210:213], v[28:31]
	v_mfma_f32_16x16x32_bf16 v[24:27], v[170:173], v[210:213], v[24:27]
	v_mfma_f32_16x16x32_bf16 v[12:15], v[142:145], v[224:227], v[12:15]
	v_mfma_f32_16x16x32_bf16 v[8:11], v[170:173], v[224:227], v[8:11]
	v_mfma_f32_16x16x32_bf16 v[60:63], v[146:149], v[198:201], v[60:63]
	v_mfma_f32_16x16x32_bf16 v[56:59], v[174:177], v[198:201], v[56:59]
	v_mfma_f32_16x16x32_bf16 v[44:47], v[146:149], v[206:209], v[44:47]
	v_mfma_f32_16x16x32_bf16 v[40:43], v[174:177], v[206:209], v[40:43]
	v_mfma_f32_16x16x32_bf16 v[28:31], v[146:149], v[220:223], v[28:31]
	v_mfma_f32_16x16x32_bf16 v[24:27], v[174:177], v[220:223], v[24:27]
	v_mfma_f32_16x16x32_bf16 v[12:15], v[146:149], v[228:231], v[12:15]
	v_mfma_f32_16x16x32_bf16 v[8:11], v[174:177], v[228:231], v[8:11]
	v_mfma_f32_16x16x32_bf16 v[52:55], v[178:181], v[194:197], v[52:55]
	v_mfma_f32_16x16x32_bf16 v[48:51], v[186:189], v[194:197], v[48:51]
	v_mfma_f32_16x16x32_bf16 v[36:39], v[178:181], v[202:205], v[36:39]
	v_mfma_f32_16x16x32_bf16 v[32:35], v[186:189], v[202:205], v[32:35]
	v_mfma_f32_16x16x32_bf16 v[20:23], v[178:181], v[210:213], v[20:23]
	v_mfma_f32_16x16x32_bf16 v[16:19], v[186:189], v[210:213], v[16:19]
	v_mfma_f32_16x16x32_bf16 v[4:7], v[178:181], v[224:227], v[4:7]
	v_mfma_f32_16x16x32_bf16 v[0:3], v[186:189], v[224:227], v[0:3]
	v_mfma_f32_16x16x32_bf16 v[52:55], v[182:185], v[198:201], v[52:55]
	v_mfma_f32_16x16x32_bf16 v[48:51], v[190:193], v[198:201], v[48:51]
	v_mfma_f32_16x16x32_bf16 v[36:39], v[182:185], v[206:209], v[36:39]
	v_mfma_f32_16x16x32_bf16 v[32:35], v[190:193], v[206:209], v[32:35]
	v_mfma_f32_16x16x32_bf16 v[20:23], v[182:185], v[220:223], v[20:23]
	v_mfma_f32_16x16x32_bf16 v[16:19], v[190:193], v[220:223], v[16:19]
	v_mfma_f32_16x16x32_bf16 v[4:7], v[182:185], v[228:231], v[4:7]
	v_mfma_f32_16x16x32_bf16 v[0:3], v[190:193], v[228:231], v[0:3]
	s_setprio 0
	s_barrier
	s_add_i32 s44, 0, 0x18000
	s_add_i32 s45, 0, 0x1c000
	v_add_u32_e32 v174, s44, v140
	v_add_u32_e32 v190, s45, v140
	ds_read_b128 v[142:145], v174
	ds_read_b128 v[146:149], v174 offset:1024
	ds_read_b128 v[170:173], v174 offset:2048
	ds_read_b128 v[174:177], v174 offset:3072
	ds_read_b128 v[178:181], v190
	ds_read_b128 v[182:185], v190 offset:1024
	ds_read_b128 v[186:189], v190 offset:2048
	ds_read_b128 v[190:193], v190 offset:3072
	s_add_u32 s38, s38, 0x80000
	s_addc_u32 s39, s39, 0
	s_mov_b32 m0, s28
	v_lshl_add_u64 v[236:237], s[38:39], 0, v[132:133]
	ds_read_b128 v[194:197], v141 offset:32768
	ds_read_b128 v[198:201], v141 offset:33792
	ds_read_b128 v[202:205], v141 offset:34816
	ds_read_b128 v[206:209], v141 offset:35840
	ds_read_b128 v[210:213], v141 offset:36864
	ds_read_b128 v[220:223], v141 offset:37888
	ds_read_b128 v[224:227], v141 offset:38912
	ds_read_b128 v[228:231], v141 offset:39936
	global_load_lds_dwordx4 v[236:237], off
	v_lshl_add_u64 v[236:237], s[38:39], 0, v[130:131]
	s_mov_b32 m0, s29
	s_nop 0
	global_load_lds_dwordx4 v[236:237], off
	s_waitcnt vmcnt(8)
	s_waitcnt lgkmcnt(0)
	s_setprio 1
	s_barrier
	v_mfma_f32_16x16x32_bf16 v[124:127], v[142:145], v[194:197], v[124:127]
	v_mfma_f32_16x16x32_bf16 v[120:123], v[170:173], v[194:197], v[120:123]
	v_mfma_f32_16x16x32_bf16 v[108:111], v[142:145], v[202:205], v[108:111]
	v_mfma_f32_16x16x32_bf16 v[104:107], v[170:173], v[202:205], v[104:107]
	v_mfma_f32_16x16x32_bf16 v[92:95], v[142:145], v[210:213], v[92:95]
	v_mfma_f32_16x16x32_bf16 v[88:91], v[170:173], v[210:213], v[88:91]
	v_mfma_f32_16x16x32_bf16 v[76:79], v[142:145], v[224:227], v[76:79]
	v_mfma_f32_16x16x32_bf16 v[72:75], v[170:173], v[224:227], v[72:75]
	v_mfma_f32_16x16x32_bf16 v[124:127], v[146:149], v[198:201], v[124:127]
	v_mfma_f32_16x16x32_bf16 v[120:123], v[174:177], v[198:201], v[120:123]
	v_mfma_f32_16x16x32_bf16 v[108:111], v[146:149], v[206:209], v[108:111]
	v_mfma_f32_16x16x32_bf16 v[104:107], v[174:177], v[206:209], v[104:107]
	v_mfma_f32_16x16x32_bf16 v[92:95], v[146:149], v[220:223], v[92:95]
	v_mfma_f32_16x16x32_bf16 v[88:91], v[174:177], v[220:223], v[88:91]
	v_mfma_f32_16x16x32_bf16 v[76:79], v[146:149], v[228:231], v[76:79]
	v_mfma_f32_16x16x32_bf16 v[72:75], v[174:177], v[228:231], v[72:75]
	v_mfma_f32_16x16x32_bf16 v[116:119], v[178:181], v[194:197], v[116:119]
	v_mfma_f32_16x16x32_bf16 v[112:115], v[186:189], v[194:197], v[112:115]
	v_mfma_f32_16x16x32_bf16 v[100:103], v[178:181], v[202:205], v[100:103]
	v_mfma_f32_16x16x32_bf16 v[96:99], v[186:189], v[202:205], v[96:99]
	v_mfma_f32_16x16x32_bf16 v[84:87], v[178:181], v[210:213], v[84:87]
	v_mfma_f32_16x16x32_bf16 v[80:83], v[186:189], v[210:213], v[80:83]
	v_mfma_f32_16x16x32_bf16 v[68:71], v[178:181], v[224:227], v[68:71]
	v_mfma_f32_16x16x32_bf16 v[64:67], v[186:189], v[224:227], v[64:67]
	v_mfma_f32_16x16x32_bf16 v[116:119], v[182:185], v[198:201], v[116:119]
	v_mfma_f32_16x16x32_bf16 v[112:115], v[190:193], v[198:201], v[112:115]
	v_mfma_f32_16x16x32_bf16 v[100:103], v[182:185], v[206:209], v[100:103]
	v_mfma_f32_16x16x32_bf16 v[96:99], v[190:193], v[206:209], v[96:99]
	v_mfma_f32_16x16x32_bf16 v[84:87], v[182:185], v[220:223], v[84:87]
	v_mfma_f32_16x16x32_bf16 v[80:83], v[190:193], v[220:223], v[80:83]
	v_mfma_f32_16x16x32_bf16 v[68:71], v[182:185], v[228:231], v[68:71]
	v_mfma_f32_16x16x32_bf16 v[64:67], v[190:193], v[228:231], v[64:67]
	s_setprio 0
	s_barrier
; #define PG8_STAGE(bufoff, gbase, voff) do { _Pragma("unroll") for (int _i = 0; _i < 2; ++_i) \
;         __builtin_amdgcn_global_load_lds((const unsigned*)((const char*)(gbase) + (voff)[_i]), (PG8_LAS unsigned*)(lds + (bufoff) + ldsw + _i * 8192), 16, 0, 0); } while (0)
; #define PG8_LDA(dst, b, h) do { _Pragma("unroll") for (int m = 0; m < 4; ++m) _Pragma("unroll") for (int k = 0; k < 2; ++k) dst[m][k] = *(const PG8_LAS bf16x8*)(lds + PG8_SA(b, h) + aoff + m * 2048 + k * 1024); } while (0)
; #define PG8_MMA(ai, bj, At, Bt) do { __builtin_amdgcn_s_setprio(1); _Pragma("unroll") for (int m = 0; m < 4; ++m) _Pragma("unroll") for (int n = 0; n < 2; ++n) _Pragma("unroll") for (int k = 0; k < 2; ++k) \
;         acc[ai][bj][m][n] = __builtin_amdgcn_mfma_f32_16x16x32_bf16(Bt[n][k], At[m][k], acc[ai][bj][m][n], 0, 0, 0); __builtin_amdgcn_s_setprio(0); } while (0)
; #define PG8_WAIT_V(n) asm volatile("s_waitcnt vmcnt(" #n ")" ::: "memory")
; #define PG8_WAIT_L(n) asm volatile("s_waitcnt lgkmcnt(" #n ")" ::: "memory")
; #define PG8_BAR __builtin_amdgcn_s_barrier()
; #define PG8_SCHED __builtin_amdgcn_sched_barrier(0)
; template <class Epi, class Sched, bool ALIGN_EPI = false, bool SP2 = false>
; __device__ __forceinline__ void gemm_phase(PG8_LAS unsigned char* lds, const Gemm g, const Sched& S, const Epi& E) {
;     ...
;             PG8_LDA(At, 1, 1); PG8_STAGE(PG8_SB(1, 0), b3, voffB); PG8_STAGE(PG8_SB(1, 1), b3 + hstep, voffB); PG8_STAGE(PG8_SA(1, 0), a3, voffA);
;             PG8_WAIT_V(8); PG8_WAIT_L(0); PG8_BAR; PG8_MMA(1, 0, At, B0); PG8_MMA(1, 1, At, B1); PG8_BAR; PG8_SCHED;
	s_add_i32 s38, s44, s26
	v_lshl_add_u64 v[150:151], v[150:151], 0, s[90:91]
	s_mov_b32 m0, s38
	ds_read_b128 v[194:197], v141 offset:49152
	ds_read_b128 v[198:201], v141 offset:50176
	ds_read_b128 v[202:205], v141 offset:51200
	ds_read_b128 v[206:209], v141 offset:52224
	ds_read_b128 v[210:213], v141 offset:53248
	ds_read_b128 v[220:223], v141 offset:54272
	ds_read_b128 v[224:227], v141 offset:55296
	ds_read_b128 v[228:231], v141 offset:56320
	global_load_lds_dwordx4 v[150:151], off
	s_add_i32 m0, s38, 0x2000
	s_add_u32 s18, s18, 0x80080
	v_lshl_add_u64 v[150:151], v[214:215], 0, s[90:91]
	s_addc_u32 s19, s19, 0
	s_add_i32 s38, s45, s26
	global_load_lds_dwordx4 v[150:151], off
	v_lshl_add_u64 v[150:151], s[18:19], 0, v[152:153]
	s_mov_b32 m0, s38
	s_nop 0
	global_load_lds_dwordx4 v[150:151], off
	v_lshl_add_u64 v[150:151], s[18:19], 0, v[128:129]
	s_add_i32 m0, s38, 0x2000
	s_nop 0
	global_load_lds_dwordx4 v[150:151], off
	v_lshl_add_u64 v[150:151], v[232:233], 0, s[90:91]
	s_mov_b32 m0, s33
	s_nop 0
	global_load_lds_dwordx4 v[150:151], off
	v_lshl_add_u64 v[150:151], v[234:235], 0, s[90:91]
	s_mov_b32 m0, s40
	s_nop 0
	global_load_lds_dwordx4 v[150:151], off
	s_waitcnt vmcnt(8)
	s_waitcnt lgkmcnt(0)
	s_setprio 1
	s_barrier
	v_mfma_f32_16x16x32_bf16 v[60:63], v[142:145], v[194:197], v[60:63]
	v_mfma_f32_16x16x32_bf16 v[56:59], v[170:173], v[194:197], v[56:59]
	v_mfma_f32_16x16x32_bf16 v[44:47], v[142:145], v[202:205], v[44:47]
	v_mfma_f32_16x16x32_bf16 v[40:43], v[170:173], v[202:205], v[40:43]
	v_mfma_f32_16x16x32_bf16 v[28:31], v[142:145], v[210:213], v[28:31]
	v_mfma_f32_16x16x32_bf16 v[24:27], v[170:173], v[210:213], v[24:27]
	v_mfma_f32_16x16x32_bf16 v[12:15], v[142:145], v[224:227], v[12:15]
	v_mfma_f32_16x16x32_bf16 v[8:11], v[170:173], v[224:227], v[8:11]
	v_mfma_f32_16x16x32_bf16 v[60:63], v[146:149], v[198:201], v[60:63]
	v_mfma_f32_16x16x32_bf16 v[56:59], v[174:177], v[198:201], v[56:59]
	v_mfma_f32_16x16x32_bf16 v[44:47], v[146:149], v[206:209], v[44:47]
	v_mfma_f32_16x16x32_bf16 v[40:43], v[174:177], v[206:209], v[40:43]
	v_mfma_f32_16x16x32_bf16 v[28:31], v[146:149], v[220:223], v[28:31]
	v_mfma_f32_16x16x32_bf16 v[24:27], v[174:177], v[220:223], v[24:27]
	v_mfma_f32_16x16x32_bf16 v[12:15], v[146:149], v[228:231], v[12:15]
	v_mfma_f32_16x16x32_bf16 v[8:11], v[174:177], v[228:231], v[8:11]
	v_mfma_f32_16x16x32_bf16 v[52:55], v[178:181], v[194:197], v[52:55]
	v_mfma_f32_16x16x32_bf16 v[48:51], v[186:189], v[194:197], v[48:51]
	v_mfma_f32_16x16x32_bf16 v[36:39], v[178:181], v[202:205], v[36:39]
	v_mfma_f32_16x16x32_bf16 v[32:35], v[186:189], v[202:205], v[32:35]
	v_mfma_f32_16x16x32_bf16 v[20:23], v[178:181], v[210:213], v[20:23]
	v_mfma_f32_16x16x32_bf16 v[16:19], v[186:189], v[210:213], v[16:19]
	v_mfma_f32_16x16x32_bf16 v[4:7], v[178:181], v[224:227], v[4:7]
	v_mfma_f32_16x16x32_bf16 v[0:3], v[186:189], v[224:227], v[0:3]
	v_mfma_f32_16x16x32_bf16 v[52:55], v[182:185], v[198:201], v[52:55]
	v_mfma_f32_16x16x32_bf16 v[48:51], v[190:193], v[198:201], v[48:51]
	v_mfma_f32_16x16x32_bf16 v[36:39], v[182:185], v[206:209], v[36:39]
	v_mfma_f32_16x16x32_bf16 v[32:35], v[190:193], v[206:209], v[32:35]
	v_mfma_f32_16x16x32_bf16 v[20:23], v[182:185], v[220:223], v[20:23]
	v_mfma_f32_16x16x32_bf16 v[16:19], v[190:193], v[220:223], v[16:19]
	v_mfma_f32_16x16x32_bf16 v[4:7], v[182:185], v[228:231], v[4:7]
	v_mfma_f32_16x16x32_bf16 v[0:3], v[190:193], v[228:231], v[0:3]
	s_setprio 0
	s_barrier
	s_add_i32 s43, s43, 2
	s_add_u32 s16, s16, 0x100
	s_addc_u32 s17, s17, 0
	s_cmp_gt_u32 s43, 29
	s_cbranch_scc0 .LBB0_291
	s_cmpk_lt_u32 s25, 0x100
	s_cbranch_scc0 .LBB0_294
	s_barrier

; #define PG8_STAGE(bufoff, gbase, voff) do { _Pragma("unroll") for (int _i = 0; _i < 2; ++_i) \
;         __builtin_amdgcn_global_load_lds((const unsigned*)((const char*)(gbase) + (voff)[_i]), (PG8_LAS unsigned*)(lds + (bufoff) + ldsw + _i * 8192), 16, 0, 0); } while (0)
; #define PG8_LDA(dst, b, h) do { _Pragma("unroll") for (int m = 0; m < 4; ++m) _Pragma("unroll") for (int k = 0; k < 2; ++k) dst[m][k] = *(const PG8_LAS bf16x8*)(lds + PG8_SA(b, h) + aoff + m * 2048 + k * 1024); } while (0)
; #define PG8_LDB(dst, b, h) do { _Pragma("unroll") for (int n = 0; n < 2; ++n) _Pragma("unroll") for (int k = 0; k < 2; ++k) dst[n][k] = *(const PG8_LAS bf16x8*)(lds + PG8_SB(b, h) + boff + n * 2048 + k * 1024); } while (0)
; #define PG8_MMA(ai, bj, At, Bt) do { __builtin_amdgcn_s_setprio(1); _Pragma("unroll") for (int m = 0; m < 4; ++m) _Pragma("unroll") for (int n = 0; n < 2; ++n) _Pragma("unroll") for (int k = 0; k < 2; ++k) \
;         acc[ai][bj][m][n] = __builtin_amdgcn_mfma_f32_16x16x32_bf16(Bt[n][k], At[m][k], acc[ai][bj][m][n], 0, 0, 0); __builtin_amdgcn_s_setprio(0); } while (0)
; #define PG8_WAIT_V(n) asm volatile("s_waitcnt vmcnt(" #n ")" ::: "memory")
; #define PG8_WAIT_L(n) asm volatile("s_waitcnt lgkmcnt(" #n ")" ::: "memory")
; template <class Epi, class Sched, bool ALIGN_EPI = false, bool SP2 = false>
; __device__ __forceinline__ void gemm_phase(PG8_LAS unsigned char* lds, const Gemm g, const Sched& S, const Epi& E) {
;     ...
;             const bool last = (t == nt - 2);
;             const char* a1 = cA + (size_t)(t + 1) * kstep;
;             const char* a2 = last ? nA : cA + (size_t)(t + 2) * kstep; const char* b2 = last ? nB : cB + (size_t)(t + 2) * kstep;
;             const char* a3 = a2 + kstep; const char* b3 = b2 + kstep;
;             if (last && has_next) S.a_ready(nxt);
;             if constexpr (SP2) {
;             PG8_LDB(B0, 0, 0); PG8_LDB(B1, 0, 1); PG8_SCHED; PG8_LDA(At, 0, 0); PG8_STAGE(PG8_SA(1, 1), a1 + hstep, voffA);
;             PG8_WAIT_V(8); PG8_WAIT_L(0); PG8_BAR; PG8_MMA(0, 0, At, B0); PG8_MMA(0, 1, At, B1); PG8_BAR; PG8_SCHED;
;             PG8_LDA(At, 0, 1); PG8_STAGE(PG8_SB(0, 0), b2, voffB); PG8_STAGE(PG8_SB(0, 1), b2 + hstep, voffB); PG8_STAGE(PG8_SA(0, 0), a2, voffA);
;             PG8_WAIT_V(8); PG8_WAIT_L(0); PG8_BAR; PG8_MMA(1, 0, At, B0); PG8_MMA(1, 1, At, B1); PG8_BAR; PG8_SCHED;
.LBB0_349:
	s_or_b32 s4, s48, 1
	s_add_i32 s48, s48, 2
	s_mov_b32 s49, s5
	s_lshl_b64 s[58:59], s[4:5], 7
	s_lshl_b64 s[82:83], s[48:49], 7
	s_add_u32 s4, s14, s82
	s_addc_u32 s33, s15, s83
	s_and_b64 s[56:57], s[54:55], exec
	s_cselect_b32 s57, s45, s33
	s_cselect_b32 s56, s44, s4
	s_add_u32 s4, s16, s82
	s_addc_u32 s33, s17, s83
	s_and_b64 s[54:55], s[54:55], exec
	s_cselect_b32 s55, s47, s33
	s_cselect_b32 s54, s46, s4
	s_add_i32 s4, 0, 0x10000
	v_add_u32_e32 v150, s4, v135
	s_add_i32 s33, 0, 0x14000
	ds_read_b128 v[138:141], v150
	ds_read_b128 v[142:145], v150 offset:1024
	ds_read_b128 v[146:149], v150 offset:2048
	ds_read_b128 v[170:173], v150 offset:3072
	v_add_u32_e32 v150, s33, v135
	ds_read_b128 v[174:177], v150
	ds_read_b128 v[178:181], v150 offset:1024
	ds_read_b128 v[182:185], v150 offset:2048
	ds_read_b128 v[186:189], v150 offset:3072
	s_add_u32 s58, s25, s58
	s_addc_u32 s59, s29, s59
	v_lshl_add_u64 v[150:151], s[58:59], 0, v[128:129]
	s_add_i32 m0, s69, 0xc000
	ds_read_b128 v[190:193], v137
	ds_read_b128 v[194:197], v137 offset:1024
	ds_read_b128 v[198:201], v137 offset:2048
	ds_read_b128 v[202:205], v137 offset:3072
	ds_read_b128 v[206:209], v137 offset:4096
	ds_read_b128 v[210:213], v137 offset:5120
	ds_read_b128 v[220:223], v137 offset:6144
	ds_read_b128 v[224:227], v137 offset:7168
	global_load_lds_dwordx4 v[150:151], off
	v_lshl_add_u64 v[150:151], s[58:59], 0, v[130:131]
	s_add_i32 m0, s69, 0xe000
	s_nop 0
	global_load_lds_dwordx4 v[150:151], off
	s_waitcnt vmcnt(8)
	s_waitcnt lgkmcnt(0)
	s_setprio 1
	s_barrier
	v_mfma_f32_16x16x32_bf16 v[124:127], v[138:141], v[190:193], v[124:127]
	v_mfma_f32_16x16x32_bf16 v[120:123], v[146:149], v[190:193], v[120:123]
	v_mfma_f32_16x16x32_bf16 v[116:119], v[138:141], v[198:201], v[116:119]
	v_mfma_f32_16x16x32_bf16 v[112:115], v[146:149], v[198:201], v[112:115]
	v_mfma_f32_16x16x32_bf16 v[108:111], v[138:141], v[206:209], v[108:111]
	v_mfma_f32_16x16x32_bf16 v[104:107], v[146:149], v[206:209], v[104:107]
	v_mfma_f32_16x16x32_bf16 v[100:103], v[138:141], v[220:223], v[100:103]
	v_mfma_f32_16x16x32_bf16 v[96:99], v[146:149], v[220:223], v[96:99]
	v_mfma_f32_16x16x32_bf16 v[124:127], v[142:145], v[194:197], v[124:127]
	v_mfma_f32_16x16x32_bf16 v[120:123], v[170:173], v[194:197], v[120:123]
	v_mfma_f32_16x16x32_bf16 v[116:119], v[142:145], v[202:205], v[116:119]
	v_mfma_f32_16x16x32_bf16 v[112:115], v[170:173], v[202:205], v[112:115]
	v_mfma_f32_16x16x32_bf16 v[108:111], v[142:145], v[210:213], v[108:111]
	v_mfma_f32_16x16x32_bf16 v[104:107], v[170:173], v[210:213], v[104:107]
	v_mfma_f32_16x16x32_bf16 v[100:103], v[142:145], v[224:227], v[100:103]
	v_mfma_f32_16x16x32_bf16 v[96:99], v[170:173], v[224:227], v[96:99]
	v_mfma_f32_16x16x32_bf16 v[92:95], v[174:177], v[190:193], v[92:95]
	v_mfma_f32_16x16x32_bf16 v[88:91], v[182:185], v[190:193], v[88:91]
	v_mfma_f32_16x16x32_bf16 v[84:87], v[174:177], v[198:201], v[84:87]
	v_mfma_f32_16x16x32_bf16 v[80:83], v[182:185], v[198:201], v[80:83]
	v_mfma_f32_16x16x32_bf16 v[76:79], v[174:177], v[206:209], v[76:79]
	v_mfma_f32_16x16x32_bf16 v[72:75], v[182:185], v[206:209], v[72:75]
	v_mfma_f32_16x16x32_bf16 v[68:71], v[174:177], v[220:223], v[68:71]
	v_mfma_f32_16x16x32_bf16 v[64:67], v[182:185], v[220:223], v[64:67]
	v_mfma_f32_16x16x32_bf16 v[92:95], v[178:181], v[194:197], v[92:95]
	v_mfma_f32_16x16x32_bf16 v[88:91], v[186:189], v[194:197], v[88:91]
	v_mfma_f32_16x16x32_bf16 v[84:87], v[178:181], v[202:205], v[84:87]
	v_mfma_f32_16x16x32_bf16 v[80:83], v[186:189], v[202:205], v[80:83]
	v_mfma_f32_16x16x32_bf16 v[76:79], v[178:181], v[210:213], v[76:79]
	v_mfma_f32_16x16x32_bf16 v[72:75], v[186:189], v[210:213], v[72:75]
	v_mfma_f32_16x16x32_bf16 v[68:71], v[178:181], v[224:227], v[68:71]
	v_mfma_f32_16x16x32_bf16 v[64:67], v[186:189], v[224:227], v[64:67]
	s_setprio 0
	s_barrier
	s_add_i32 s4, s4, s68
	v_lshl_add_u64 v[150:151], s[54:55], 0, v[152:153]
	s_mov_b32 m0, s4
	ds_read_b128 v[190:193], v137 offset:16384
	ds_read_b128 v[194:197], v137 offset:17408
	ds_read_b128 v[198:201], v137 offset:18432
	ds_read_b128 v[202:205], v137 offset:19456
	ds_read_b128 v[206:209], v137 offset:20480
	ds_read_b128 v[210:213], v137 offset:21504
	ds_read_b128 v[220:223], v137 offset:22528
	ds_read_b128 v[224:227], v137 offset:23552
	global_load_lds_dwordx4 v[150:151], off
	s_add_i32 m0, s4, 0x2000
	v_lshl_add_u64 v[214:215], s[54:55], 0, v[132:133]
	s_add_u32 s54, s54, s66
	s_addc_u32 s55, s55, 0
	s_add_i32 s4, s33, s68
	global_load_lds_dwordx4 v[214:215], off
	v_lshl_add_u64 v[228:229], s[54:55], 0, v[152:153]
	s_mov_b32 m0, s4
	v_lshl_add_u64 v[230:231], s[54:55], 0, v[132:133]
	global_load_lds_dwordx4 v[228:229], off
	s_add_i32 m0, s4, 0x2000
	v_lshl_add_u64 v[232:233], s[56:57], 0, v[128:129]
	global_load_lds_dwordx4 v[230:231], off
	s_mov_b32 m0, s69
	v_lshl_add_u64 v[234:235], s[56:57], 0, v[130:131]
	global_load_lds_dwordx4 v[232:233], off
	s_mov_b32 m0, s70
	s_nop 0
	global_load_lds_dwordx4 v[234:235], off
	s_waitcnt vmcnt(8)
	s_waitcnt lgkmcnt(0)
	s_setprio 1
	s_barrier
; #define PG8_STAGE(bufoff, gbase, voff) do { _Pragma("unroll") for (int _i = 0; _i < 2; ++_i) \
;         __builtin_amdgcn_global_load_lds((const unsigned*)((const char*)(gbase) + (voff)[_i]), (PG8_LAS unsigned*)(lds + (bufoff) + ldsw + _i * 8192), 16, 0, 0); } while (0)
; #define PG8_LDA(dst, b, h) do { _Pragma("unroll") for (int m = 0; m < 4; ++m) _Pragma("unroll") for (int k = 0; k < 2; ++k) dst[m][k] = *(const PG8_LAS bf16x8*)(lds + PG8_SA(b, h) + aoff + m * 2048 + k * 1024); } while (0)
; #define PG8_LDB(dst, b, h) do { _Pragma("unroll") for (int n = 0; n < 2; ++n) _Pragma("unroll") for (int k = 0; k < 2; ++k) dst[n][k] = *(const PG8_LAS bf16x8*)(lds + PG8_SB(b, h) + boff + n * 2048 + k * 1024); } while (0)
; #define PG8_MMA(ai, bj, At, Bt) do { __builtin_amdgcn_s_setprio(1); _Pragma("unroll") for (int m = 0; m < 4; ++m) _Pragma("unroll") for (int n = 0; n < 2; ++n) _Pragma("unroll") for (int k = 0; k < 2; ++k) \
;         acc[ai][bj][m][n] = __builtin_amdgcn_mfma_f32_16x16x32_bf16(Bt[n][k], At[m][k], acc[ai][bj][m][n], 0, 0, 0); __builtin_amdgcn_s_setprio(0); } while (0)
; #define PG8_WAIT_V(n) asm volatile("s_waitcnt vmcnt(" #n ")" ::: "memory")
; #define PG8_WAIT_L(n) asm volatile("s_waitcnt lgkmcnt(" #n ")" ::: "memory")
; #define PG8_BAR __builtin_amdgcn_s_barrier()
; #define PG8_SCHED __builtin_amdgcn_sched_barrier(0)
; template <class Epi, class Sched, bool ALIGN_EPI = false, bool SP2 = false>
; __device__ __forceinline__ void gemm_phase(PG8_LAS unsigned char* lds, const Gemm g, const Sched& S, const Epi& E) {
;     ...
;             PG8_WAIT_V(8); PG8_WAIT_L(0); PG8_BAR; PG8_MMA(1, 0, At, B0); PG8_MMA(1, 1, At, B1); PG8_BAR; PG8_SCHED;
;             PG8_LDB(B0, 1, 0); PG8_LDB(B1, 1, 1); PG8_SCHED; PG8_LDA(At, 1, 0); PG8_STAGE(PG8_SA(0, 1), a2 + hstep, voffA);
;             PG8_WAIT_V(8); PG8_WAIT_L(0); PG8_BAR; PG8_MMA(0, 0, At, B0); PG8_MMA(0, 1, At, B1); PG8_BAR; PG8_SCHED;
	v_mfma_f32_16x16x32_bf16 v[60:63], v[138:141], v[190:193], v[60:63]
	v_mfma_f32_16x16x32_bf16 v[56:59], v[146:149], v[190:193], v[56:59]
	v_mfma_f32_16x16x32_bf16 v[52:55], v[138:141], v[198:201], v[52:55]
	v_mfma_f32_16x16x32_bf16 v[48:51], v[146:149], v[198:201], v[48:51]
	v_mfma_f32_16x16x32_bf16 v[44:47], v[138:141], v[206:209], v[44:47]
	v_mfma_f32_16x16x32_bf16 v[40:43], v[146:149], v[206:209], v[40:43]
	v_mfma_f32_16x16x32_bf16 v[36:39], v[138:141], v[220:223], v[36:39]
	v_mfma_f32_16x16x32_bf16 v[32:35], v[146:149], v[220:223], v[32:35]
	v_mfma_f32_16x16x32_bf16 v[60:63], v[142:145], v[194:197], v[60:63]
	v_mfma_f32_16x16x32_bf16 v[56:59], v[170:173], v[194:197], v[56:59]
	v_mfma_f32_16x16x32_bf16 v[52:55], v[142:145], v[202:205], v[52:55]
	v_mfma_f32_16x16x32_bf16 v[48:51], v[170:173], v[202:205], v[48:51]
	v_mfma_f32_16x16x32_bf16 v[44:47], v[142:145], v[210:213], v[44:47]
	v_mfma_f32_16x16x32_bf16 v[40:43], v[170:173], v[210:213], v[40:43]
	v_mfma_f32_16x16x32_bf16 v[36:39], v[142:145], v[224:227], v[36:39]
	v_mfma_f32_16x16x32_bf16 v[32:35], v[170:173], v[224:227], v[32:35]
	v_mfma_f32_16x16x32_bf16 v[28:31], v[174:177], v[190:193], v[28:31]
	v_mfma_f32_16x16x32_bf16 v[24:27], v[182:185], v[190:193], v[24:27]
	v_mfma_f32_16x16x32_bf16 v[20:23], v[174:177], v[198:201], v[20:23]
	v_mfma_f32_16x16x32_bf16 v[16:19], v[182:185], v[198:201], v[16:19]
	v_mfma_f32_16x16x32_bf16 v[12:15], v[174:177], v[206:209], v[12:15]
	v_mfma_f32_16x16x32_bf16 v[8:11], v[182:185], v[206:209], v[8:11]
	v_mfma_f32_16x16x32_bf16 v[4:7], v[174:177], v[220:223], v[4:7]
	v_mfma_f32_16x16x32_bf16 v[0:3], v[182:185], v[220:223], v[0:3]
	v_mfma_f32_16x16x32_bf16 v[28:31], v[178:181], v[194:197], v[28:31]
	v_mfma_f32_16x16x32_bf16 v[24:27], v[186:189], v[194:197], v[24:27]
	v_mfma_f32_16x16x32_bf16 v[20:23], v[178:181], v[202:205], v[20:23]
	v_mfma_f32_16x16x32_bf16 v[16:19], v[186:189], v[202:205], v[16:19]
	v_mfma_f32_16x16x32_bf16 v[12:15], v[178:181], v[210:213], v[12:15]
	v_mfma_f32_16x16x32_bf16 v[8:11], v[186:189], v[210:213], v[8:11]
	v_mfma_f32_16x16x32_bf16 v[4:7], v[178:181], v[224:227], v[4:7]
	v_mfma_f32_16x16x32_bf16 v[0:3], v[186:189], v[224:227], v[0:3]
	s_setprio 0
	s_barrier
	s_add_i32 s4, 0, 0x18000
	s_add_i32 s33, 0, 0x1c000
	v_add_u32_e32 v170, s4, v135
	v_add_u32_e32 v186, s33, v135
	ds_read_b128 v[138:141], v170
	ds_read_b128 v[142:145], v170 offset:1024
	ds_read_b128 v[146:149], v170 offset:2048
	ds_read_b128 v[170:173], v170 offset:3072
	ds_read_b128 v[174:177], v186
	ds_read_b128 v[178:181], v186 offset:1024
	ds_read_b128 v[182:185], v186 offset:2048
	ds_read_b128 v[186:189], v186 offset:3072
	s_add_u32 s54, s56, s66
	s_addc_u32 s55, s57, 0
	s_mov_b32 m0, s71
	v_lshl_add_u64 v[236:237], s[54:55], 0, v[128:129]
	ds_read_b128 v[190:193], v137 offset:32768
	ds_read_b128 v[194:197], v137 offset:33792
	ds_read_b128 v[198:201], v137 offset:34816
	ds_read_b128 v[202:205], v137 offset:35840
	ds_read_b128 v[206:209], v137 offset:36864
	ds_read_b128 v[210:213], v137 offset:37888
	ds_read_b128 v[220:223], v137 offset:38912
	ds_read_b128 v[224:227], v137 offset:39936
	global_load_lds_dwordx4 v[236:237], off
	v_lshl_add_u64 v[236:237], s[54:55], 0, v[130:131]
	s_mov_b32 m0, s72
	s_nop 0
	global_load_lds_dwordx4 v[236:237], off
	s_waitcnt vmcnt(8)
	s_waitcnt lgkmcnt(0)
	s_setprio 1
	s_barrier
	v_mfma_f32_16x16x32_bf16 v[124:127], v[138:141], v[190:193], v[124:127]
	v_mfma_f32_16x16x32_bf16 v[120:123], v[146:149], v[190:193], v[120:123]
	v_mfma_f32_16x16x32_bf16 v[116:119], v[138:141], v[198:201], v[116:119]
	v_mfma_f32_16x16x32_bf16 v[112:115], v[146:149], v[198:201], v[112:115]
	v_mfma_f32_16x16x32_bf16 v[108:111], v[138:141], v[206:209], v[108:111]
	v_mfma_f32_16x16x32_bf16 v[104:107], v[146:149], v[206:209], v[104:107]
	v_mfma_f32_16x16x32_bf16 v[100:103], v[138:141], v[220:223], v[100:103]
	v_mfma_f32_16x16x32_bf16 v[96:99], v[146:149], v[220:223], v[96:99]
	v_mfma_f32_16x16x32_bf16 v[124:127], v[142:145], v[194:197], v[124:127]
	v_mfma_f32_16x16x32_bf16 v[120:123], v[170:173], v[194:197], v[120:123]
	v_mfma_f32_16x16x32_bf16 v[116:119], v[142:145], v[202:205], v[116:119]
	v_mfma_f32_16x16x32_bf16 v[112:115], v[170:173], v[202:205], v[112:115]
	v_mfma_f32_16x16x32_bf16 v[108:111], v[142:145], v[210:213], v[108:111]
	v_mfma_f32_16x16x32_bf16 v[104:107], v[170:173], v[210:213], v[104:107]
	v_mfma_f32_16x16x32_bf16 v[100:103], v[142:145], v[224:227], v[100:103]
	v_mfma_f32_16x16x32_bf16 v[96:99], v[170:173], v[224:227], v[96:99]
	v_mfma_f32_16x16x32_bf16 v[92:95], v[174:177], v[190:193], v[92:95]
	v_mfma_f32_16x16x32_bf16 v[88:91], v[182:185], v[190:193], v[88:91]
	v_mfma_f32_16x16x32_bf16 v[84:87], v[174:177], v[198:201], v[84:87]
	v_mfma_f32_16x16x32_bf16 v[80:83], v[182:185], v[198:201], v[80:83]
	v_mfma_f32_16x16x32_bf16 v[76:79], v[174:177], v[206:209], v[76:79]
	v_mfma_f32_16x16x32_bf16 v[72:75], v[182:185], v[206:209], v[72:75]
	v_mfma_f32_16x16x32_bf16 v[68:71], v[174:177], v[220:223], v[68:71]
	v_mfma_f32_16x16x32_bf16 v[64:67], v[182:185], v[220:223], v[64:67]
	v_mfma_f32_16x16x32_bf16 v[92:95], v[178:181], v[194:197], v[92:95]
	v_mfma_f32_16x16x32_bf16 v[88:91], v[186:189], v[194:197], v[88:91]
	v_mfma_f32_16x16x32_bf16 v[84:87], v[178:181], v[202:205], v[84:87]
	v_mfma_f32_16x16x32_bf16 v[80:83], v[186:189], v[202:205], v[80:83]
	v_mfma_f32_16x16x32_bf16 v[76:79], v[178:181], v[210:213], v[76:79]
	v_mfma_f32_16x16x32_bf16 v[72:75], v[186:189], v[210:213], v[72:75]
	v_mfma_f32_16x16x32_bf16 v[68:71], v[178:181], v[224:227], v[68:71]
	v_mfma_f32_16x16x32_bf16 v[64:67], v[186:189], v[224:227], v[64:67]
	s_setprio 0
	s_barrier
; #define PG8_STAGE(bufoff, gbase, voff) do { _Pragma("unroll") for (int _i = 0; _i < 2; ++_i) \
;         __builtin_amdgcn_global_load_lds((const unsigned*)((const char*)(gbase) + (voff)[_i]), (PG8_LAS unsigned*)(lds + (bufoff) + ldsw + _i * 8192), 16, 0, 0); } while (0)
; #define PG8_LDA(dst, b, h) do { _Pragma("unroll") for (int m = 0; m < 4; ++m) _Pragma("unroll") for (int k = 0; k < 2; ++k) dst[m][k] = *(const PG8_LAS bf16x8*)(lds + PG8_SA(b, h) + aoff + m * 2048 + k * 1024); } while (0)
; #define PG8_MMA(ai, bj, At, Bt) do { __builtin_amdgcn_s_setprio(1); _Pragma("unroll") for (int m = 0; m < 4; ++m) _Pragma("unroll") for (int n = 0; n < 2; ++n) _Pragma("unroll") for (int k = 0; k < 2; ++k) \
;         acc[ai][bj][m][n] = __builtin_amdgcn_mfma_f32_16x16x32_bf16(Bt[n][k], At[m][k], acc[ai][bj][m][n], 0, 0, 0); __builtin_amdgcn_s_setprio(0); } while (0)
; #define PG8_WAIT_V(n) asm volatile("s_waitcnt vmcnt(" #n ")" ::: "memory")
; #define PG8_WAIT_L(n) asm volatile("s_waitcnt lgkmcnt(" #n ")" ::: "memory")
; #define PG8_BAR __builtin_amdgcn_s_barrier()
; #define PG8_SCHED __builtin_amdgcn_sched_barrier(0)
; template <class Epi, class Sched, bool ALIGN_EPI = false, bool SP2 = false>
; __device__ __forceinline__ void gemm_phase(PG8_LAS unsigned char* lds, const Gemm g, const Sched& S, const Epi& E) {
;     ...
;             PG8_LDA(At, 1, 1); PG8_STAGE(PG8_SB(1, 0), b3, voffB); PG8_STAGE(PG8_SB(1, 1), b3 + hstep, voffB); PG8_STAGE(PG8_SA(1, 0), a3, voffA);
;             PG8_WAIT_V(8); PG8_WAIT_L(0); PG8_BAR; PG8_MMA(1, 0, At, B0); PG8_MMA(1, 1, At, B1); PG8_BAR; PG8_SCHED;
	s_add_i32 s4, s4, s68
	v_lshl_add_u64 v[150:151], v[150:151], 0, s[90:91]
	s_mov_b32 m0, s4
	ds_read_b128 v[190:193], v137 offset:49152
	ds_read_b128 v[194:197], v137 offset:50176
	ds_read_b128 v[198:201], v137 offset:51200
	ds_read_b128 v[202:205], v137 offset:52224
	ds_read_b128 v[206:209], v137 offset:53248
	ds_read_b128 v[210:213], v137 offset:54272
	ds_read_b128 v[220:223], v137 offset:55296
	ds_read_b128 v[224:227], v137 offset:56320
	global_load_lds_dwordx4 v[150:151], off
	v_lshl_add_u64 v[150:151], v[214:215], 0, s[90:91]
	s_add_i32 m0, s4, 0x2000
	s_add_i32 s4, s33, s68
	global_load_lds_dwordx4 v[150:151], off
	v_lshl_add_u64 v[150:151], v[228:229], 0, s[90:91]
	s_mov_b32 m0, s4
	s_nop 0
	global_load_lds_dwordx4 v[150:151], off
	v_lshl_add_u64 v[150:151], v[230:231], 0, s[90:91]
	s_add_i32 m0, s4, 0x2000
	s_nop 0
	global_load_lds_dwordx4 v[150:151], off
	v_lshl_add_u64 v[150:151], v[232:233], 0, s[90:91]
	s_mov_b32 m0, s75
	s_nop 0
	global_load_lds_dwordx4 v[150:151], off
	v_lshl_add_u64 v[150:151], v[234:235], 0, s[90:91]
	s_mov_b32 m0, s76
	s_nop 0
	global_load_lds_dwordx4 v[150:151], off
	s_waitcnt vmcnt(8)
	s_waitcnt lgkmcnt(0)
	s_setprio 1
	s_barrier
	v_mfma_f32_16x16x32_bf16 v[60:63], v[138:141], v[190:193], v[60:63]
	v_mfma_f32_16x16x32_bf16 v[56:59], v[146:149], v[190:193], v[56:59]
	v_mfma_f32_16x16x32_bf16 v[52:55], v[138:141], v[198:201], v[52:55]
	v_mfma_f32_16x16x32_bf16 v[48:51], v[146:149], v[198:201], v[48:51]
	v_mfma_f32_16x16x32_bf16 v[44:47], v[138:141], v[206:209], v[44:47]
	v_mfma_f32_16x16x32_bf16 v[40:43], v[146:149], v[206:209], v[40:43]
	v_mfma_f32_16x16x32_bf16 v[36:39], v[138:141], v[220:223], v[36:39]
	v_mfma_f32_16x16x32_bf16 v[32:35], v[146:149], v[220:223], v[32:35]
	v_mfma_f32_16x16x32_bf16 v[60:63], v[142:145], v[194:197], v[60:63]
	v_mfma_f32_16x16x32_bf16 v[56:59], v[170:173], v[194:197], v[56:59]
	v_mfma_f32_16x16x32_bf16 v[52:55], v[142:145], v[202:205], v[52:55]
	v_mfma_f32_16x16x32_bf16 v[48:51], v[170:173], v[202:205], v[48:51]
	v_mfma_f32_16x16x32_bf16 v[44:47], v[142:145], v[210:213], v[44:47]
	v_mfma_f32_16x16x32_bf16 v[40:43], v[170:173], v[210:213], v[40:43]
	v_mfma_f32_16x16x32_bf16 v[36:39], v[142:145], v[224:227], v[36:39]
	v_mfma_f32_16x16x32_bf16 v[32:35], v[170:173], v[224:227], v[32:35]
	v_mfma_f32_16x16x32_bf16 v[28:31], v[174:177], v[190:193], v[28:31]
	v_mfma_f32_16x16x32_bf16 v[24:27], v[182:185], v[190:193], v[24:27]
	v_mfma_f32_16x16x32_bf16 v[20:23], v[174:177], v[198:201], v[20:23]
	v_mfma_f32_16x16x32_bf16 v[16:19], v[182:185], v[198:201], v[16:19]
	v_mfma_f32_16x16x32_bf16 v[12:15], v[174:177], v[206:209], v[12:15]
	v_mfma_f32_16x16x32_bf16 v[8:11], v[182:185], v[206:209], v[8:11]
	v_mfma_f32_16x16x32_bf16 v[4:7], v[174:177], v[220:223], v[4:7]
	v_mfma_f32_16x16x32_bf16 v[0:3], v[182:185], v[220:223], v[0:3]
	v_mfma_f32_16x16x32_bf16 v[28:31], v[178:181], v[194:197], v[28:31]
	v_mfma_f32_16x16x32_bf16 v[24:27], v[186:189], v[194:197], v[24:27]
	v_mfma_f32_16x16x32_bf16 v[20:23], v[178:181], v[202:205], v[20:23]
	v_mfma_f32_16x16x32_bf16 v[16:19], v[186:189], v[202:205], v[16:19]
	v_mfma_f32_16x16x32_bf16 v[12:15], v[178:181], v[210:213], v[12:15]
	v_mfma_f32_16x16x32_bf16 v[8:11], v[186:189], v[210:213], v[8:11]
	v_mfma_f32_16x16x32_bf16 v[4:7], v[178:181], v[224:227], v[4:7]
	v_mfma_f32_16x16x32_bf16 v[0:3], v[186:189], v[224:227], v[0:3]
	s_setprio 0
	s_barrier
	s_cmp_ge_u32 s48, s73
	s_cbranch_scc1 .LBB0_356

; #define PG8_STAGE(bufoff, gbase, voff) do { _Pragma("unroll") for (int _i = 0; _i < 2; ++_i) \
;         __builtin_amdgcn_global_load_lds((const unsigned*)((const char*)(gbase) + (voff)[_i]), (PG8_LAS unsigned*)(lds + (bufoff) + ldsw + _i * 8192), 16, 0, 0); } while (0)
; #define PG8_LDA(dst, b, h) do { _Pragma("unroll") for (int m = 0; m < 4; ++m) _Pragma("unroll") for (int k = 0; k < 2; ++k) dst[m][k] = *(const PG8_LAS bf16x8*)(lds + PG8_SA(b, h) + aoff + m * 2048 + k * 1024); } while (0)
; #define PG8_LDB(dst, b, h) do { _Pragma("unroll") for (int n = 0; n < 2; ++n) _Pragma("unroll") for (int k = 0; k < 2; ++k) dst[n][k] = *(const PG8_LAS bf16x8*)(lds + PG8_SB(b, h) + boff + n * 2048 + k * 1024); } while (0)
; #define PG8_MMA(ai, bj, At, Bt) do { __builtin_amdgcn_s_setprio(1); _Pragma("unroll") for (int m = 0; m < 4; ++m) _Pragma("unroll") for (int n = 0; n < 2; ++n) _Pragma("unroll") for (int k = 0; k < 2; ++k) \
;         acc[ai][bj][m][n] = __builtin_amdgcn_mfma_f32_16x16x32_bf16(Bt[n][k], At[m][k], acc[ai][bj][m][n], 0, 0, 0); __builtin_amdgcn_s_setprio(0); } while (0)
; #define PG8_WAIT_V(n) asm volatile("s_waitcnt vmcnt(" #n ")" ::: "memory")
; #define PG8_WAIT_L(n) asm volatile("s_waitcnt lgkmcnt(" #n ")" ::: "memory")
; template <class Epi, class Sched, bool ALIGN_EPI = false, bool SP2 = false>
; __device__ __forceinline__ void gemm_phase(PG8_LAS unsigned char* lds, const Gemm g, const Sched& S, const Epi& E) {
;     ...
;             const bool last = (t == nt - 2);
;             const char* a1 = cA + (size_t)(t + 1) * kstep;
;             const char* a2 = last ? nA : cA + (size_t)(t + 2) * kstep; const char* b2 = last ? nB : cB + (size_t)(t + 2) * kstep;
;             const char* a3 = a2 + kstep; const char* b3 = b2 + kstep;
;             if (last && has_next) S.a_ready(nxt);
;             if constexpr (SP2) {
;             PG8_LDB(B0, 0, 0); PG8_LDB(B1, 0, 1); PG8_SCHED; PG8_LDA(At, 0, 0); PG8_STAGE(PG8_SA(1, 1), a1 + hstep, voffA);
;             PG8_WAIT_V(8); PG8_WAIT_L(0); PG8_BAR; PG8_MMA(0, 0, At, B0); PG8_MMA(0, 1, At, B1); PG8_BAR; PG8_SCHED;
;             PG8_LDA(At, 0, 1); PG8_STAGE(PG8_SB(0, 0), b2, voffB); PG8_STAGE(PG8_SB(0, 1), b2 + hstep, voffB); PG8_STAGE(PG8_SA(0, 0), a2, voffA);
;             PG8_WAIT_V(8); PG8_WAIT_L(0); PG8_BAR; PG8_MMA(1, 0, At, B0); PG8_MMA(1, 1, At, B1); PG8_BAR; PG8_SCHED;
.LBB0_431:
	s_add_u32 s54, s42, s52
	s_addc_u32 s55, s43, s53
	s_add_u32 s54, s54, 0x100
	s_addc_u32 s55, s55, 0
	s_add_u32 s75, s29, s52
	s_addc_u32 s76, s33, s53
	s_cmpk_eq_i32 s52, 0xf00
	s_cselect_b32 s57, s25, s55
	s_cselect_b32 s56, s47, s54
	s_cselect_b32 s55, s45, s76
	s_cselect_b32 s54, s73, s75
	s_add_i32 s75, 0, 0x10000
	v_add_u32_e32 v152, s75, v145
	s_add_i32 s78, 0, 0x14000
	ds_read_b128 v[148:151], v152
	ds_read_b128 v[170:173], v152 offset:1024
	ds_read_b128 v[174:177], v152 offset:2048
	ds_read_b128 v[178:181], v152 offset:3072
	v_add_u32_e32 v152, s78, v145
	ds_read_b128 v[182:185], v152
	ds_read_b128 v[186:189], v152 offset:1024
	ds_read_b128 v[190:193], v152 offset:2048
	ds_read_b128 v[194:197], v152 offset:3072
	s_add_u32 s76, s42, s52
	s_addc_u32 s77, s43, s53
	s_add_u32 s76, s76, 0x80080
	s_addc_u32 s77, s77, 0
	s_add_i32 m0, s15, 0xc000
	ds_read_b128 v[198:201], v147
	ds_read_b128 v[202:205], v147 offset:1024
	ds_read_b128 v[206:209], v147 offset:2048
	ds_read_b128 v[210:213], v147 offset:3072
	ds_read_b128 v[220:223], v147 offset:4096
	ds_read_b128 v[224:227], v147 offset:5120
	ds_read_b128 v[228:231], v147 offset:6144
	ds_read_b128 v[232:235], v147 offset:7168
	global_load_lds_dwordx4 v136, s[76:77]
	s_add_i32 m0, s15, 0xe000
	s_nop 0
	global_load_lds_dwordx4 v138, s[76:77]
	s_waitcnt vmcnt(8)
	s_waitcnt lgkmcnt(0)
	s_setprio 1
	s_barrier
	v_mfma_f32_16x16x32_bf16 v[124:127], v[148:151], v[198:201], v[124:127]
	v_mfma_f32_16x16x32_bf16 v[120:123], v[174:177], v[198:201], v[120:123]
	v_mfma_f32_16x16x32_bf16 v[116:119], v[148:151], v[206:209], v[116:119]
	v_mfma_f32_16x16x32_bf16 v[112:115], v[174:177], v[206:209], v[112:115]
	v_mfma_f32_16x16x32_bf16 v[108:111], v[148:151], v[220:223], v[108:111]
	v_mfma_f32_16x16x32_bf16 v[104:107], v[174:177], v[220:223], v[104:107]
	v_mfma_f32_16x16x32_bf16 v[100:103], v[148:151], v[228:231], v[100:103]
	v_mfma_f32_16x16x32_bf16 v[96:99], v[174:177], v[228:231], v[96:99]
	v_mfma_f32_16x16x32_bf16 v[124:127], v[170:173], v[202:205], v[124:127]
	v_mfma_f32_16x16x32_bf16 v[120:123], v[178:181], v[202:205], v[120:123]
	v_mfma_f32_16x16x32_bf16 v[116:119], v[170:173], v[210:213], v[116:119]
	v_mfma_f32_16x16x32_bf16 v[112:115], v[178:181], v[210:213], v[112:115]
	v_mfma_f32_16x16x32_bf16 v[108:111], v[170:173], v[224:227], v[108:111]
	v_mfma_f32_16x16x32_bf16 v[104:107], v[178:181], v[224:227], v[104:107]
	v_mfma_f32_16x16x32_bf16 v[100:103], v[170:173], v[232:235], v[100:103]
	v_mfma_f32_16x16x32_bf16 v[96:99], v[178:181], v[232:235], v[96:99]
	v_mfma_f32_16x16x32_bf16 v[92:95], v[182:185], v[198:201], v[92:95]
	v_mfma_f32_16x16x32_bf16 v[88:91], v[190:193], v[198:201], v[88:91]
	v_mfma_f32_16x16x32_bf16 v[84:87], v[182:185], v[206:209], v[84:87]
	v_mfma_f32_16x16x32_bf16 v[80:83], v[190:193], v[206:209], v[80:83]
	v_mfma_f32_16x16x32_bf16 v[76:79], v[182:185], v[220:223], v[76:79]
	v_mfma_f32_16x16x32_bf16 v[72:75], v[190:193], v[220:223], v[72:75]
	v_mfma_f32_16x16x32_bf16 v[68:71], v[182:185], v[228:231], v[68:71]
	v_mfma_f32_16x16x32_bf16 v[64:67], v[190:193], v[228:231], v[64:67]
	v_mfma_f32_16x16x32_bf16 v[92:95], v[186:189], v[202:205], v[92:95]
	v_mfma_f32_16x16x32_bf16 v[88:91], v[194:197], v[202:205], v[88:91]
	v_mfma_f32_16x16x32_bf16 v[84:87], v[186:189], v[210:213], v[84:87]
	v_mfma_f32_16x16x32_bf16 v[80:83], v[194:197], v[210:213], v[80:83]
	v_mfma_f32_16x16x32_bf16 v[76:79], v[186:189], v[224:227], v[76:79]
	v_mfma_f32_16x16x32_bf16 v[72:75], v[194:197], v[224:227], v[72:75]
	v_mfma_f32_16x16x32_bf16 v[68:71], v[186:189], v[232:235], v[68:71]
	v_mfma_f32_16x16x32_bf16 v[64:67], v[194:197], v[232:235], v[64:67]
	s_setprio 0
	s_barrier
	s_add_i32 s75, s75, s65
	s_mov_b32 m0, s75
	ds_read_b128 v[198:201], v147 offset:16384
	ds_read_b128 v[202:205], v147 offset:17408
	ds_read_b128 v[206:209], v147 offset:18432
	ds_read_b128 v[210:213], v147 offset:19456
	ds_read_b128 v[220:223], v147 offset:20480
	ds_read_b128 v[224:227], v147 offset:21504
	ds_read_b128 v[228:231], v147 offset:22528
	ds_read_b128 v[232:235], v147 offset:23552
	global_load_lds_dwordx4 v130, s[54:55]
	s_add_i32 m0, s75, 0x2000
	s_add_u32 s76, s54, 0x80000
	s_addc_u32 s77, s55, 0
	s_add_i32 s75, s78, s65
	global_load_lds_dwordx4 v134, s[54:55]
	s_mov_b32 m0, s75
	s_nop 0
	global_load_lds_dwordx4 v130, s[76:77]
	s_add_i32 m0, s75, 0x2000
	s_nop 0
	global_load_lds_dwordx4 v134, s[76:77]
	s_mov_b32 m0, s15
	s_nop 0
	global_load_lds_dwordx4 v128, s[56:57]
	s_mov_b32 m0, s17
	s_nop 0
	global_load_lds_dwordx4 v132, s[56:57]
	s_waitcnt vmcnt(8)
	s_waitcnt lgkmcnt(0)
	s_setprio 1
	s_barrier
; #define PG8_STAGE(bufoff, gbase, voff) do { _Pragma("unroll") for (int _i = 0; _i < 2; ++_i) \
;         __builtin_amdgcn_global_load_lds((const unsigned*)((const char*)(gbase) + (voff)[_i]), (PG8_LAS unsigned*)(lds + (bufoff) + ldsw + _i * 8192), 16, 0, 0); } while (0)
; #define PG8_LDA(dst, b, h) do { _Pragma("unroll") for (int m = 0; m < 4; ++m) _Pragma("unroll") for (int k = 0; k < 2; ++k) dst[m][k] = *(const PG8_LAS bf16x8*)(lds + PG8_SA(b, h) + aoff + m * 2048 + k * 1024); } while (0)
; #define PG8_LDB(dst, b, h) do { _Pragma("unroll") for (int n = 0; n < 2; ++n) _Pragma("unroll") for (int k = 0; k < 2; ++k) dst[n][k] = *(const PG8_LAS bf16x8*)(lds + PG8_SB(b, h) + boff + n * 2048 + k * 1024); } while (0)
; #define PG8_MMA(ai, bj, At, Bt) do { __builtin_amdgcn_s_setprio(1); _Pragma("unroll") for (int m = 0; m < 4; ++m) _Pragma("unroll") for (int n = 0; n < 2; ++n) _Pragma("unroll") for (int k = 0; k < 2; ++k) \
;         acc[ai][bj][m][n] = __builtin_amdgcn_mfma_f32_16x16x32_bf16(Bt[n][k], At[m][k], acc[ai][bj][m][n], 0, 0, 0); __builtin_amdgcn_s_setprio(0); } while (0)
; #define PG8_WAIT_V(n) asm volatile("s_waitcnt vmcnt(" #n ")" ::: "memory")
; #define PG8_WAIT_L(n) asm volatile("s_waitcnt lgkmcnt(" #n ")" ::: "memory")
; #define PG8_BAR __builtin_amdgcn_s_barrier()
; #define PG8_SCHED __builtin_amdgcn_sched_barrier(0)
; template <class Epi, class Sched, bool ALIGN_EPI = false, bool SP2 = false>
; __device__ __forceinline__ void gemm_phase(PG8_LAS unsigned char* lds, const Gemm g, const Sched& S, const Epi& E) {
;     ...
;             PG8_WAIT_V(8); PG8_WAIT_L(0); PG8_BAR; PG8_MMA(1, 0, At, B0); PG8_MMA(1, 1, At, B1); PG8_BAR; PG8_SCHED;
;             PG8_LDB(B0, 1, 0); PG8_LDB(B1, 1, 1); PG8_SCHED; PG8_LDA(At, 1, 0); PG8_STAGE(PG8_SA(0, 1), a2 + hstep, voffA);
;             PG8_WAIT_V(8); PG8_WAIT_L(0); PG8_BAR; PG8_MMA(0, 0, At, B0); PG8_MMA(0, 1, At, B1); PG8_BAR; PG8_SCHED;
	v_mfma_f32_16x16x32_bf16 v[60:63], v[148:151], v[198:201], v[60:63]
	v_mfma_f32_16x16x32_bf16 v[56:59], v[174:177], v[198:201], v[56:59]
	v_mfma_f32_16x16x32_bf16 v[52:55], v[148:151], v[206:209], v[52:55]
	v_mfma_f32_16x16x32_bf16 v[48:51], v[174:177], v[206:209], v[48:51]
	v_mfma_f32_16x16x32_bf16 v[44:47], v[148:151], v[220:223], v[44:47]
	v_mfma_f32_16x16x32_bf16 v[40:43], v[174:177], v[220:223], v[40:43]
	v_mfma_f32_16x16x32_bf16 v[36:39], v[148:151], v[228:231], v[36:39]
	v_mfma_f32_16x16x32_bf16 v[32:35], v[174:177], v[228:231], v[32:35]
	v_mfma_f32_16x16x32_bf16 v[60:63], v[170:173], v[202:205], v[60:63]
	v_mfma_f32_16x16x32_bf16 v[56:59], v[178:181], v[202:205], v[56:59]
	v_mfma_f32_16x16x32_bf16 v[52:55], v[170:173], v[210:213], v[52:55]
	v_mfma_f32_16x16x32_bf16 v[48:51], v[178:181], v[210:213], v[48:51]
	v_mfma_f32_16x16x32_bf16 v[44:47], v[170:173], v[224:227], v[44:47]
	v_mfma_f32_16x16x32_bf16 v[40:43], v[178:181], v[224:227], v[40:43]
	v_mfma_f32_16x16x32_bf16 v[36:39], v[170:173], v[232:235], v[36:39]
	v_mfma_f32_16x16x32_bf16 v[32:35], v[178:181], v[232:235], v[32:35]
	v_mfma_f32_16x16x32_bf16 v[28:31], v[182:185], v[198:201], v[28:31]
	v_mfma_f32_16x16x32_bf16 v[24:27], v[190:193], v[198:201], v[24:27]
	v_mfma_f32_16x16x32_bf16 v[20:23], v[182:185], v[206:209], v[20:23]
	v_mfma_f32_16x16x32_bf16 v[16:19], v[190:193], v[206:209], v[16:19]
	v_mfma_f32_16x16x32_bf16 v[12:15], v[182:185], v[220:223], v[12:15]
	v_mfma_f32_16x16x32_bf16 v[8:11], v[190:193], v[220:223], v[8:11]
	v_mfma_f32_16x16x32_bf16 v[4:7], v[182:185], v[228:231], v[4:7]
	v_mfma_f32_16x16x32_bf16 v[0:3], v[190:193], v[228:231], v[0:3]
	v_mfma_f32_16x16x32_bf16 v[28:31], v[186:189], v[202:205], v[28:31]
	v_mfma_f32_16x16x32_bf16 v[24:27], v[194:197], v[202:205], v[24:27]
	v_mfma_f32_16x16x32_bf16 v[20:23], v[186:189], v[210:213], v[20:23]
	v_mfma_f32_16x16x32_bf16 v[16:19], v[194:197], v[210:213], v[16:19]
	v_mfma_f32_16x16x32_bf16 v[12:15], v[186:189], v[224:227], v[12:15]
	v_mfma_f32_16x16x32_bf16 v[8:11], v[194:197], v[224:227], v[8:11]
	v_mfma_f32_16x16x32_bf16 v[4:7], v[186:189], v[232:235], v[4:7]
	v_mfma_f32_16x16x32_bf16 v[0:3], v[194:197], v[232:235], v[0:3]
	s_setprio 0
	s_barrier
	s_add_i32 s75, 0, 0x18000
	v_add_u32_e32 v152, s75, v145
	s_add_i32 s76, 0, 0x1c000
	ds_read_b128 v[148:151], v152
	ds_read_b128 v[170:173], v152 offset:1024
	ds_read_b128 v[174:177], v152 offset:2048
	ds_read_b128 v[178:181], v152 offset:3072
	v_add_u32_e32 v152, s76, v145
	ds_read_b128 v[182:185], v152
	ds_read_b128 v[186:189], v152 offset:1024
	ds_read_b128 v[190:193], v152 offset:2048
	ds_read_b128 v[194:197], v152 offset:3072
	s_add_u32 s56, s56, 0x80000
	s_addc_u32 s57, s57, 0
	s_mov_b32 m0, s68
	ds_read_b128 v[198:201], v147 offset:32768
	ds_read_b128 v[202:205], v147 offset:33792
	ds_read_b128 v[206:209], v147 offset:34816
	ds_read_b128 v[210:213], v147 offset:35840
	ds_read_b128 v[220:223], v147 offset:36864
	ds_read_b128 v[224:227], v147 offset:37888
	ds_read_b128 v[228:231], v147 offset:38912
	ds_read_b128 v[232:235], v147 offset:39936
	global_load_lds_dwordx4 v128, s[56:57]
	s_mov_b32 m0, s69
	s_nop 0
	global_load_lds_dwordx4 v132, s[56:57]
	s_waitcnt vmcnt(8)
	s_waitcnt lgkmcnt(0)
	s_setprio 1
	s_barrier
	v_mfma_f32_16x16x32_bf16 v[124:127], v[148:151], v[198:201], v[124:127]
	v_mfma_f32_16x16x32_bf16 v[120:123], v[174:177], v[198:201], v[120:123]
	v_mfma_f32_16x16x32_bf16 v[116:119], v[148:151], v[206:209], v[116:119]
	v_mfma_f32_16x16x32_bf16 v[112:115], v[174:177], v[206:209], v[112:115]
	v_mfma_f32_16x16x32_bf16 v[108:111], v[148:151], v[220:223], v[108:111]
	v_mfma_f32_16x16x32_bf16 v[104:107], v[174:177], v[220:223], v[104:107]
	v_mfma_f32_16x16x32_bf16 v[100:103], v[148:151], v[228:231], v[100:103]
	v_mfma_f32_16x16x32_bf16 v[96:99], v[174:177], v[228:231], v[96:99]
	v_mfma_f32_16x16x32_bf16 v[124:127], v[170:173], v[202:205], v[124:127]
	v_mfma_f32_16x16x32_bf16 v[120:123], v[178:181], v[202:205], v[120:123]
	v_mfma_f32_16x16x32_bf16 v[116:119], v[170:173], v[210:213], v[116:119]
	v_mfma_f32_16x16x32_bf16 v[112:115], v[178:181], v[210:213], v[112:115]
	v_mfma_f32_16x16x32_bf16 v[108:111], v[170:173], v[224:227], v[108:111]
	v_mfma_f32_16x16x32_bf16 v[104:107], v[178:181], v[224:227], v[104:107]
	v_mfma_f32_16x16x32_bf16 v[100:103], v[170:173], v[232:235], v[100:103]
	v_mfma_f32_16x16x32_bf16 v[96:99], v[178:181], v[232:235], v[96:99]
	v_mfma_f32_16x16x32_bf16 v[92:95], v[182:185], v[198:201], v[92:95]
	v_mfma_f32_16x16x32_bf16 v[88:91], v[190:193], v[198:201], v[88:91]
	v_mfma_f32_16x16x32_bf16 v[84:87], v[182:185], v[206:209], v[84:87]
	v_mfma_f32_16x16x32_bf16 v[80:83], v[190:193], v[206:209], v[80:83]
	v_mfma_f32_16x16x32_bf16 v[76:79], v[182:185], v[220:223], v[76:79]
	v_mfma_f32_16x16x32_bf16 v[72:75], v[190:193], v[220:223], v[72:75]
	v_mfma_f32_16x16x32_bf16 v[68:71], v[182:185], v[228:231], v[68:71]
	v_mfma_f32_16x16x32_bf16 v[64:67], v[190:193], v[228:231], v[64:67]
	v_mfma_f32_16x16x32_bf16 v[92:95], v[186:189], v[202:205], v[92:95]
	v_mfma_f32_16x16x32_bf16 v[88:91], v[194:197], v[202:205], v[88:91]
	v_mfma_f32_16x16x32_bf16 v[84:87], v[186:189], v[210:213], v[84:87]
	v_mfma_f32_16x16x32_bf16 v[80:83], v[194:197], v[210:213], v[80:83]
	v_mfma_f32_16x16x32_bf16 v[76:79], v[186:189], v[224:227], v[76:79]
	v_mfma_f32_16x16x32_bf16 v[72:75], v[194:197], v[224:227], v[72:75]
	v_mfma_f32_16x16x32_bf16 v[68:71], v[186:189], v[232:235], v[68:71]
	v_mfma_f32_16x16x32_bf16 v[64:67], v[194:197], v[232:235], v[64:67]
	s_setprio 0
	s_barrier
; #define PG8_STAGE(bufoff, gbase, voff) do { _Pragma("unroll") for (int _i = 0; _i < 2; ++_i) \
;         __builtin_amdgcn_global_load_lds((const unsigned*)((const char*)(gbase) + (voff)[_i]), (PG8_LAS unsigned*)(lds + (bufoff) + ldsw + _i * 8192), 16, 0, 0); } while (0)
; #define PG8_LDA(dst, b, h) do { _Pragma("unroll") for (int m = 0; m < 4; ++m) _Pragma("unroll") for (int k = 0; k < 2; ++k) dst[m][k] = *(const PG8_LAS bf16x8*)(lds + PG8_SA(b, h) + aoff + m * 2048 + k * 1024); } while (0)
; #define PG8_MMA(ai, bj, At, Bt) do { __builtin_amdgcn_s_setprio(1); _Pragma("unroll") for (int m = 0; m < 4; ++m) _Pragma("unroll") for (int n = 0; n < 2; ++n) _Pragma("unroll") for (int k = 0; k < 2; ++k) \
;         acc[ai][bj][m][n] = __builtin_amdgcn_mfma_f32_16x16x32_bf16(Bt[n][k], At[m][k], acc[ai][bj][m][n], 0, 0, 0); __builtin_amdgcn_s_setprio(0); } while (0)
; #define PG8_WAIT_V(n) asm volatile("s_waitcnt vmcnt(" #n ")" ::: "memory")
; #define PG8_WAIT_L(n) asm volatile("s_waitcnt lgkmcnt(" #n ")" ::: "memory")
; #define PG8_BAR __builtin_amdgcn_s_barrier()
; #define PG8_SCHED __builtin_amdgcn_sched_barrier(0)
; template <class Epi, class Sched, bool ALIGN_EPI = false, bool SP2 = false>
; __device__ __forceinline__ void gemm_phase(PG8_LAS unsigned char* lds, const Gemm g, const Sched& S, const Epi& E) {
;     ...
;             PG8_LDA(At, 1, 1); PG8_STAGE(PG8_SB(1, 0), b3, voffB); PG8_STAGE(PG8_SB(1, 1), b3 + hstep, voffB); PG8_STAGE(PG8_SA(1, 0), a3, voffA);
;             PG8_WAIT_V(8); PG8_WAIT_L(0); PG8_BAR; PG8_MMA(1, 0, At, B0); PG8_MMA(1, 1, At, B1); PG8_BAR; PG8_SCHED;
	s_add_i32 s78, s75, s65
	s_add_u32 s54, s54, 0x80
	s_addc_u32 s55, s55, 0
	s_mov_b32 m0, s78
	ds_read_b128 v[198:201], v147 offset:49152
	ds_read_b128 v[202:205], v147 offset:50176
	ds_read_b128 v[206:209], v147 offset:51200
	ds_read_b128 v[210:213], v147 offset:52224
	ds_read_b128 v[220:223], v147 offset:53248
	ds_read_b128 v[224:227], v147 offset:54272
	ds_read_b128 v[228:231], v147 offset:55296
	ds_read_b128 v[232:235], v147 offset:56320
	global_load_lds_dwordx4 v130, s[54:55]
	s_add_i32 m0, s78, 0x2000
	s_add_i32 s78, s76, s65
	global_load_lds_dwordx4 v134, s[54:55]
	s_add_u32 s54, s54, 0x80000
	s_addc_u32 s55, s55, 0
	s_mov_b32 m0, s78
	s_nop 0
	global_load_lds_dwordx4 v130, s[54:55]
	s_add_i32 m0, s78, 0x2000
	s_sub_u32 s56, s56, 0x7ff80
	s_subb_u32 s57, s57, 0
	global_load_lds_dwordx4 v134, s[54:55]
	s_mov_b32 m0, s70
	s_nop 0
	global_load_lds_dwordx4 v128, s[56:57]
	s_mov_b32 m0, s71
	s_nop 0
	global_load_lds_dwordx4 v132, s[56:57]
	s_waitcnt vmcnt(8)
	s_waitcnt lgkmcnt(0)
	s_setprio 1
	s_barrier
	v_mfma_f32_16x16x32_bf16 v[60:63], v[148:151], v[198:201], v[60:63]
	v_mfma_f32_16x16x32_bf16 v[56:59], v[174:177], v[198:201], v[56:59]
	v_mfma_f32_16x16x32_bf16 v[52:55], v[148:151], v[206:209], v[52:55]
	v_mfma_f32_16x16x32_bf16 v[48:51], v[174:177], v[206:209], v[48:51]
	v_mfma_f32_16x16x32_bf16 v[44:47], v[148:151], v[220:223], v[44:47]
	v_mfma_f32_16x16x32_bf16 v[40:43], v[174:177], v[220:223], v[40:43]
	v_mfma_f32_16x16x32_bf16 v[36:39], v[148:151], v[228:231], v[36:39]
	v_mfma_f32_16x16x32_bf16 v[32:35], v[174:177], v[228:231], v[32:35]
	v_mfma_f32_16x16x32_bf16 v[60:63], v[170:173], v[202:205], v[60:63]
	v_mfma_f32_16x16x32_bf16 v[56:59], v[178:181], v[202:205], v[56:59]
	v_mfma_f32_16x16x32_bf16 v[52:55], v[170:173], v[210:213], v[52:55]
	v_mfma_f32_16x16x32_bf16 v[48:51], v[178:181], v[210:213], v[48:51]
	v_mfma_f32_16x16x32_bf16 v[44:47], v[170:173], v[224:227], v[44:47]
	v_mfma_f32_16x16x32_bf16 v[40:43], v[178:181], v[224:227], v[40:43]
	v_mfma_f32_16x16x32_bf16 v[36:39], v[170:173], v[232:235], v[36:39]
	v_mfma_f32_16x16x32_bf16 v[32:35], v[178:181], v[232:235], v[32:35]
	v_mfma_f32_16x16x32_bf16 v[28:31], v[182:185], v[198:201], v[28:31]
	v_mfma_f32_16x16x32_bf16 v[24:27], v[190:193], v[198:201], v[24:27]
	v_mfma_f32_16x16x32_bf16 v[20:23], v[182:185], v[206:209], v[20:23]
	v_mfma_f32_16x16x32_bf16 v[16:19], v[190:193], v[206:209], v[16:19]
	v_mfma_f32_16x16x32_bf16 v[12:15], v[182:185], v[220:223], v[12:15]
	v_mfma_f32_16x16x32_bf16 v[8:11], v[190:193], v[220:223], v[8:11]
	v_mfma_f32_16x16x32_bf16 v[4:7], v[182:185], v[228:231], v[4:7]
	v_mfma_f32_16x16x32_bf16 v[0:3], v[190:193], v[228:231], v[0:3]
	v_mfma_f32_16x16x32_bf16 v[28:31], v[186:189], v[202:205], v[28:31]
	v_mfma_f32_16x16x32_bf16 v[24:27], v[194:197], v[202:205], v[24:27]
	v_mfma_f32_16x16x32_bf16 v[20:23], v[186:189], v[210:213], v[20:23]
	v_mfma_f32_16x16x32_bf16 v[16:19], v[194:197], v[210:213], v[16:19]
	v_mfma_f32_16x16x32_bf16 v[12:15], v[186:189], v[224:227], v[12:15]
	v_mfma_f32_16x16x32_bf16 v[8:11], v[194:197], v[224:227], v[8:11]
	v_mfma_f32_16x16x32_bf16 v[4:7], v[186:189], v[232:235], v[4:7]
	v_mfma_f32_16x16x32_bf16 v[0:3], v[194:197], v[232:235], v[0:3]
	s_setprio 0
	s_barrier
	s_add_i32 s74, s74, 2
	s_add_u32 s52, s52, 0x100
	s_addc_u32 s53, s53, 0
	s_cmp_gt_u32 s74, 29
	s_cbranch_scc0 .LBB0_431
	s_and_b64 vcc, exec, s[26:27]
	s_cbranch_vccz .LBB0_434
	s_barrier
